# RWKV scan: per-row v operand of two consecutive steps fetched by one ds_read2st64_b32; lgkmcnt waits recomputed
# speedup vs baseline: 1.0047x; 1.0047x over previous
.Lrw_fast:
	s_setprio 3
	s_and_b32 s89, s64, 1
	s_mul_i32 s89, s89, 0xc000
	v_lshl_add_u32 v112, s28, 5, v81
	v_lshl_add_u32 v124, v84, 2, s89
	v_lshl_add_u32 v135, v112, 2, s89
	ds_read_b128 v[76:79], v124 offset:272
	ds_read_b128 v[72:75], v124 offset:256
	ds_read_b128 v[68:71], v124 offset:512
	ds_read_b128 v[56:59], v124 offset:528
	ds_read2st64_b32 v[160:161], v135 offset0:5 offset1:11
	ds_read_b128 v[64:67], v124 offset:768
	ds_read_b128 v[60:63], v124 offset:784
	ds_read_b128 v[48:51], v124 offset:0
	ds_read_b128 v[40:43], v124 offset:16
	ds_read_b128 v[52:55], v124 offset:1040
	ds_read_b128 v[44:47], v124 offset:1024
	ds_read_b128 v[156:159], v124 offset:1808
	ds_read_b128 v[152:155], v124 offset:1792
	ds_read_b128 v[182:185], v124 offset:2048
	ds_read_b128 v[186:189], v124 offset:2064
	ds_read_b128 v[190:193], v124 offset:2304
	ds_read_b128 v[194:197], v124 offset:2320
	ds_read_b128 v[144:147], v124 offset:1536
	ds_read_b128 v[148:151], v124 offset:1552
	ds_read_b128 v[202:205], v124 offset:2576
	ds_read_b128 v[198:201], v124 offset:2560
	s_waitcnt lgkmcnt(10)
	v_pk_mul_f32 v[76:77], v[32:33], v[76:77]
	v_pk_mul_f32 v[78:79], v[34:35], v[78:79]
	v_pk_fma_f32 v[72:73], v[36:37], v[72:73], v[76:77]
	v_pk_fma_f32 v[74:75], v[38:39], v[74:75], v[78:79]
	v_pk_add_f32 v[72:73], v[72:73], v[74:75]
	v_add_f32_e32 v142, v72, v73
	s_nop 1
	v_add_f32_dpp v142, v142, v142 quad_perm:[1,0,3,2] row_mask:0xf bank_mask:0xf bound_ctrl:1
	s_nop 1
	v_add_f32_dpp v142, v142, v142 quad_perm:[2,3,0,1] row_mask:0xf bank_mask:0xf bound_ctrl:1
	s_nop 1
	v_add_f32_dpp v142, v142, v142 row_half_mirror row_mask:0xf bank_mask:0xf bound_ctrl:1
	v_pk_mul_f32 v[68:69], v[68:69], v[142:143] op_sel_hi:[1,0]
	v_pk_mul_f32 v[70:71], v[70:71], v[142:143] op_sel_hi:[1,0]
	v_pk_mul_f32 v[56:57], v[56:57], v[142:143] op_sel_hi:[1,0]
	v_pk_mul_f32 v[58:59], v[58:59], v[142:143] op_sel_hi:[1,0]
	v_pk_fma_f32 v[64:65], v[64:65], v[160:161], v[68:69] op_sel_hi:[1,0,1] neg_lo:[0,0,1] neg_hi:[0,0,1]
	v_pk_fma_f32 v[66:67], v[66:67], v[160:161], v[70:71] op_sel_hi:[1,0,1] neg_lo:[0,0,1] neg_hi:[0,0,1]
	v_pk_fma_f32 v[60:61], v[60:61], v[160:161], v[56:57] op_sel_hi:[1,0,1] neg_lo:[0,0,1] neg_hi:[0,0,1]
	v_pk_fma_f32 v[62:63], v[62:63], v[160:161], v[58:59] op_sel_hi:[1,0,1] neg_lo:[0,0,1] neg_hi:[0,0,1]
	v_pk_fma_f32 v[36:37], v[36:37], v[48:49], v[64:65]
	v_pk_fma_f32 v[38:39], v[38:39], v[50:51], v[66:67]
	v_pk_fma_f32 v[32:33], v[32:33], v[40:41], v[60:61]
	v_pk_fma_f32 v[34:35], v[34:35], v[42:43], v[62:63]
	s_waitcnt lgkmcnt(2)
	v_pk_mul_f32 v[156:157], v[32:33], v[156:157]
	v_pk_mul_f32 v[52:53], v[32:33], v[52:53]
	v_pk_mul_f32 v[158:159], v[34:35], v[158:159]
	v_pk_mul_f32 v[54:55], v[34:35], v[54:55]
	v_pk_fma_f32 v[152:153], v[36:37], v[152:153], v[156:157]
	v_pk_fma_f32 v[44:45], v[36:37], v[44:45], v[52:53]
	v_pk_fma_f32 v[154:155], v[38:39], v[154:155], v[158:159]
	v_pk_fma_f32 v[46:47], v[38:39], v[46:47], v[54:55]
	v_pk_add_f32 v[152:153], v[152:153], v[154:155]
	v_pk_add_f32 v[44:45], v[44:45], v[46:47]
	v_add_f32_e32 v142, v152, v153
	v_add_f32_e32 v143, v44, v45
	ds_read_b128 v[76:79], v124 offset:3344
	v_add_f32_dpp v142, v142, v142 quad_perm:[1,0,3,2] row_mask:0xf bank_mask:0xf bound_ctrl:1
	v_add_f32_dpp v143, v143, v143 quad_perm:[1,0,3,2] row_mask:0xf bank_mask:0xf bound_ctrl:1
	ds_read_b128 v[72:75], v124 offset:3328
	v_add_f32_dpp v142, v142, v142 quad_perm:[2,3,0,1] row_mask:0xf bank_mask:0xf bound_ctrl:1
	v_add_f32_dpp v143, v143, v143 quad_perm:[2,3,0,1] row_mask:0xf bank_mask:0xf bound_ctrl:1
	ds_read_b128 v[68:71], v124 offset:3584
	v_add_f32_dpp v142, v142, v142 row_half_mirror row_mask:0xf bank_mask:0xf bound_ctrl:1
	v_add_f32_dpp v143, v143, v143 row_half_mirror row_mask:0xf bank_mask:0xf bound_ctrl:1
	ds_read_b128 v[56:59], v124 offset:3600
	ds_read2st64_b32 v[126:127], v135 offset0:17 offset1:23
	ds_read_b128 v[64:67], v124 offset:3840
	ds_read_b128 v[60:63], v124 offset:3856
	ds_read_b128 v[48:51], v124 offset:3072
	ds_read_b128 v[40:43], v124 offset:3088
	v_pk_mul_f32 v[182:183], v[182:183], v[142:143] op_sel_hi:[1,0]
	v_pk_mul_f32 v[184:185], v[184:185], v[142:143] op_sel_hi:[1,0]
	s_mov_b32 vcc_lo, 0x1010101
	v_pk_mul_f32 v[186:187], v[186:187], v[142:143] op_sel_hi:[1,0]
	v_pk_mul_f32 v[188:189], v[188:189], v[142:143] op_sel_hi:[1,0]
	s_mov_b32 vcc_hi, 0x1010101
	v_pk_fma_f32 v[190:191], v[190:191], v[160:161], v[182:183] op_sel:[0,1,0] op_sel_hi:[1,1,1] neg_lo:[0,0,1] neg_hi:[0,0,1]
	v_pk_fma_f32 v[192:193], v[192:193], v[160:161], v[184:185] op_sel:[0,1,0] op_sel_hi:[1,1,1] neg_lo:[0,0,1] neg_hi:[0,0,1]
	v_cndmask_b32_e32 v134, v134, v143, vcc
	v_pk_fma_f32 v[194:195], v[194:195], v[160:161], v[186:187] op_sel:[0,1,0] op_sel_hi:[1,1,1] neg_lo:[0,0,1] neg_hi:[0,0,1]
	v_pk_fma_f32 v[196:197], v[196:197], v[160:161], v[188:189] op_sel:[0,1,0] op_sel_hi:[1,1,1] neg_lo:[0,0,1] neg_hi:[0,0,1]
	ds_read_b128 v[52:55], v124 offset:4112
	ds_read_b128 v[44:47], v124 offset:4096
	v_pk_fma_f32 v[36:37], v[36:37], v[144:145], v[190:191]
	v_pk_fma_f32 v[38:39], v[38:39], v[146:147], v[192:193]
	v_pk_fma_f32 v[32:33], v[32:33], v[148:149], v[194:195]
	v_pk_fma_f32 v[34:35], v[34:35], v[150:151], v[196:197]
	s_waitcnt lgkmcnt(2)
	v_pk_mul_f32 v[76:77], v[32:33], v[76:77]
	v_pk_mul_f32 v[202:203], v[32:33], v[202:203]
	v_pk_mul_f32 v[78:79], v[34:35], v[78:79]
	v_pk_mul_f32 v[204:205], v[34:35], v[204:205]
	v_pk_fma_f32 v[72:73], v[36:37], v[72:73], v[76:77]
	v_pk_fma_f32 v[198:199], v[36:37], v[198:199], v[202:203]
	v_pk_fma_f32 v[74:75], v[38:39], v[74:75], v[78:79]
	v_pk_fma_f32 v[200:201], v[38:39], v[200:201], v[204:205]
	v_pk_add_f32 v[72:73], v[72:73], v[74:75]
	v_pk_add_f32 v[198:199], v[198:199], v[200:201]
	v_add_f32_e32 v142, v72, v73
	v_add_f32_e32 v143, v198, v199
	ds_read_b128 v[156:159], v124 offset:4880
	v_add_f32_dpp v142, v142, v142 quad_perm:[1,0,3,2] row_mask:0xf bank_mask:0xf bound_ctrl:1
	v_add_f32_dpp v143, v143, v143 quad_perm:[1,0,3,2] row_mask:0xf bank_mask:0xf bound_ctrl:1
	ds_read_b128 v[152:155], v124 offset:4864
	v_add_f32_dpp v142, v142, v142 quad_perm:[2,3,0,1] row_mask:0xf bank_mask:0xf bound_ctrl:1
	v_add_f32_dpp v143, v143, v143 quad_perm:[2,3,0,1] row_mask:0xf bank_mask:0xf bound_ctrl:1
	ds_read_b128 v[182:185], v124 offset:5120
	v_add_f32_dpp v142, v142, v142 row_half_mirror row_mask:0xf bank_mask:0xf bound_ctrl:1
	v_add_f32_dpp v143, v143, v143 row_half_mirror row_mask:0xf bank_mask:0xf bound_ctrl:1
	ds_read_b128 v[186:189], v124 offset:5136
	ds_read_b128 v[190:193], v124 offset:5376
	ds_read_b128 v[194:197], v124 offset:5392
	ds_read_b128 v[144:147], v124 offset:4608
	ds_read_b128 v[148:151], v124 offset:4624
	v_pk_mul_f32 v[68:69], v[68:69], v[142:143] op_sel_hi:[1,0]
	v_pk_mul_f32 v[70:71], v[70:71], v[142:143] op_sel_hi:[1,0]
	s_lshl_b64 vcc, vcc, 1
	v_pk_mul_f32 v[56:57], v[56:57], v[142:143] op_sel_hi:[1,0]
	v_pk_mul_f32 v[58:59], v[58:59], v[142:143] op_sel_hi:[1,0]
	v_pk_fma_f32 v[64:65], v[64:65], v[126:127], v[68:69] op_sel_hi:[1,0,1] neg_lo:[0,0,1] neg_hi:[0,0,1]
	v_pk_fma_f32 v[66:67], v[66:67], v[126:127], v[70:71] op_sel_hi:[1,0,1] neg_lo:[0,0,1] neg_hi:[0,0,1]
	v_cndmask_b32_e32 v134, v134, v143, vcc
	v_pk_fma_f32 v[60:61], v[60:61], v[126:127], v[56:57] op_sel_hi:[1,0,1] neg_lo:[0,0,1] neg_hi:[0,0,1]
	v_pk_fma_f32 v[62:63], v[62:63], v[126:127], v[58:59] op_sel_hi:[1,0,1] neg_lo:[0,0,1] neg_hi:[0,0,1]
	ds_read_b128 v[202:205], v124 offset:5648
	ds_read_b128 v[198:201], v124 offset:5632
	v_pk_fma_f32 v[36:37], v[36:37], v[48:49], v[64:65]
	v_pk_fma_f32 v[38:39], v[38:39], v[50:51], v[66:67]
	v_pk_fma_f32 v[32:33], v[32:33], v[40:41], v[60:61]
	v_pk_fma_f32 v[34:35], v[34:35], v[42:43], v[62:63]
	s_waitcnt lgkmcnt(2)
	v_pk_mul_f32 v[156:157], v[32:33], v[156:157]
	v_pk_mul_f32 v[52:53], v[32:33], v[52:53]
	v_pk_mul_f32 v[158:159], v[34:35], v[158:159]
	v_pk_mul_f32 v[54:55], v[34:35], v[54:55]
	v_pk_fma_f32 v[152:153], v[36:37], v[152:153], v[156:157]
	v_pk_fma_f32 v[44:45], v[36:37], v[44:45], v[52:53]
	v_pk_fma_f32 v[154:155], v[38:39], v[154:155], v[158:159]
	v_pk_fma_f32 v[46:47], v[38:39], v[46:47], v[54:55]
	v_pk_add_f32 v[152:153], v[152:153], v[154:155]
	v_pk_add_f32 v[44:45], v[44:45], v[46:47]
	v_add_f32_e32 v142, v152, v153
	v_add_f32_e32 v143, v44, v45
	ds_read_b128 v[76:79], v124 offset:6416
	v_add_f32_dpp v142, v142, v142 quad_perm:[1,0,3,2] row_mask:0xf bank_mask:0xf bound_ctrl:1
	v_add_f32_dpp v143, v143, v143 quad_perm:[1,0,3,2] row_mask:0xf bank_mask:0xf bound_ctrl:1
	ds_read_b128 v[72:75], v124 offset:6400
	v_add_f32_dpp v142, v142, v142 quad_perm:[2,3,0,1] row_mask:0xf bank_mask:0xf bound_ctrl:1
	v_add_f32_dpp v143, v143, v143 quad_perm:[2,3,0,1] row_mask:0xf bank_mask:0xf bound_ctrl:1
	ds_read_b128 v[68:71], v124 offset:6656
	v_add_f32_dpp v142, v142, v142 row_half_mirror row_mask:0xf bank_mask:0xf bound_ctrl:1
	v_add_f32_dpp v143, v143, v143 row_half_mirror row_mask:0xf bank_mask:0xf bound_ctrl:1
	ds_read_b128 v[56:59], v124 offset:6672
	ds_read2st64_b32 v[160:161], v135 offset0:29 offset1:35
	ds_read_b128 v[64:67], v124 offset:6912
	ds_read_b128 v[60:63], v124 offset:6928
	ds_read_b128 v[48:51], v124 offset:6144
	ds_read_b128 v[40:43], v124 offset:6160
	v_pk_mul_f32 v[182:183], v[182:183], v[142:143] op_sel_hi:[1,0]
	v_pk_mul_f32 v[184:185], v[184:185], v[142:143] op_sel_hi:[1,0]
	s_lshl_b64 vcc, vcc, 1
	v_pk_mul_f32 v[186:187], v[186:187], v[142:143] op_sel_hi:[1,0]
	v_pk_mul_f32 v[188:189], v[188:189], v[142:143] op_sel_hi:[1,0]
	v_pk_fma_f32 v[190:191], v[190:191], v[126:127], v[182:183] op_sel:[0,1,0] op_sel_hi:[1,1,1] neg_lo:[0,0,1] neg_hi:[0,0,1]
	v_pk_fma_f32 v[192:193], v[192:193], v[126:127], v[184:185] op_sel:[0,1,0] op_sel_hi:[1,1,1] neg_lo:[0,0,1] neg_hi:[0,0,1]
	v_cndmask_b32_e32 v134, v134, v143, vcc
	v_pk_fma_f32 v[194:195], v[194:195], v[126:127], v[186:187] op_sel:[0,1,0] op_sel_hi:[1,1,1] neg_lo:[0,0,1] neg_hi:[0,0,1]
	v_pk_fma_f32 v[196:197], v[196:197], v[126:127], v[188:189] op_sel:[0,1,0] op_sel_hi:[1,1,1] neg_lo:[0,0,1] neg_hi:[0,0,1]
	ds_read_b128 v[52:55], v124 offset:7184
	ds_read_b128 v[44:47], v124 offset:7168
	v_pk_fma_f32 v[36:37], v[36:37], v[144:145], v[190:191]
	v_pk_fma_f32 v[38:39], v[38:39], v[146:147], v[192:193]
	v_pk_fma_f32 v[32:33], v[32:33], v[148:149], v[194:195]
	v_pk_fma_f32 v[34:35], v[34:35], v[150:151], v[196:197]
	s_waitcnt lgkmcnt(2)
	v_pk_mul_f32 v[76:77], v[32:33], v[76:77]
	v_pk_mul_f32 v[202:203], v[32:33], v[202:203]
	v_pk_mul_f32 v[78:79], v[34:35], v[78:79]
	v_pk_mul_f32 v[204:205], v[34:35], v[204:205]
	v_pk_fma_f32 v[72:73], v[36:37], v[72:73], v[76:77]
	v_pk_fma_f32 v[198:199], v[36:37], v[198:199], v[202:203]
	v_pk_fma_f32 v[74:75], v[38:39], v[74:75], v[78:79]
	v_pk_fma_f32 v[200:201], v[38:39], v[200:201], v[204:205]
	v_pk_add_f32 v[72:73], v[72:73], v[74:75]
	v_pk_add_f32 v[198:199], v[198:199], v[200:201]
	v_add_f32_e32 v142, v72, v73
	v_add_f32_e32 v143, v198, v199
	ds_read_b128 v[156:159], v124 offset:7952
	v_add_f32_dpp v142, v142, v142 quad_perm:[1,0,3,2] row_mask:0xf bank_mask:0xf bound_ctrl:1
	v_add_f32_dpp v143, v143, v143 quad_perm:[1,0,3,2] row_mask:0xf bank_mask:0xf bound_ctrl:1
	ds_read_b128 v[152:155], v124 offset:7936
	v_add_f32_dpp v142, v142, v142 quad_perm:[2,3,0,1] row_mask:0xf bank_mask:0xf bound_ctrl:1
	v_add_f32_dpp v143, v143, v143 quad_perm:[2,3,0,1] row_mask:0xf bank_mask:0xf bound_ctrl:1
	ds_read_b128 v[182:185], v124 offset:8192
	v_add_f32_dpp v142, v142, v142 row_half_mirror row_mask:0xf bank_mask:0xf bound_ctrl:1
	v_add_f32_dpp v143, v143, v143 row_half_mirror row_mask:0xf bank_mask:0xf bound_ctrl:1
	ds_read_b128 v[186:189], v124 offset:8208
	ds_read_b128 v[190:193], v124 offset:8448
	ds_read_b128 v[194:197], v124 offset:8464
	ds_read_b128 v[144:147], v124 offset:7680
	ds_read_b128 v[148:151], v124 offset:7696
	v_pk_mul_f32 v[68:69], v[68:69], v[142:143] op_sel_hi:[1,0]
	v_pk_mul_f32 v[70:71], v[70:71], v[142:143] op_sel_hi:[1,0]
	s_lshl_b64 vcc, vcc, 1
	v_pk_mul_f32 v[56:57], v[56:57], v[142:143] op_sel_hi:[1,0]
	v_pk_mul_f32 v[58:59], v[58:59], v[142:143] op_sel_hi:[1,0]
	v_pk_fma_f32 v[64:65], v[64:65], v[160:161], v[68:69] op_sel_hi:[1,0,1] neg_lo:[0,0,1] neg_hi:[0,0,1]
	v_pk_fma_f32 v[66:67], v[66:67], v[160:161], v[70:71] op_sel_hi:[1,0,1] neg_lo:[0,0,1] neg_hi:[0,0,1]
	v_cndmask_b32_e32 v134, v134, v143, vcc
	v_pk_fma_f32 v[60:61], v[60:61], v[160:161], v[56:57] op_sel_hi:[1,0,1] neg_lo:[0,0,1] neg_hi:[0,0,1]
	v_pk_fma_f32 v[62:63], v[62:63], v[160:161], v[58:59] op_sel_hi:[1,0,1] neg_lo:[0,0,1] neg_hi:[0,0,1]
	ds_read_b128 v[202:205], v124 offset:8720
	ds_read_b128 v[198:201], v124 offset:8704
	v_pk_fma_f32 v[36:37], v[36:37], v[48:49], v[64:65]
	v_pk_fma_f32 v[38:39], v[38:39], v[50:51], v[66:67]
	v_pk_fma_f32 v[32:33], v[32:33], v[40:41], v[60:61]
	v_pk_fma_f32 v[34:35], v[34:35], v[42:43], v[62:63]
	s_waitcnt lgkmcnt(2)
	v_pk_mul_f32 v[156:157], v[32:33], v[156:157]
	v_pk_mul_f32 v[52:53], v[32:33], v[52:53]
	v_pk_mul_f32 v[158:159], v[34:35], v[158:159]
	v_pk_mul_f32 v[54:55], v[34:35], v[54:55]
	v_pk_fma_f32 v[152:153], v[36:37], v[152:153], v[156:157]
	v_pk_fma_f32 v[44:45], v[36:37], v[44:45], v[52:53]
	v_pk_fma_f32 v[154:155], v[38:39], v[154:155], v[158:159]
	v_pk_fma_f32 v[46:47], v[38:39], v[46:47], v[54:55]
	v_pk_add_f32 v[152:153], v[152:153], v[154:155]
	v_pk_add_f32 v[44:45], v[44:45], v[46:47]
	v_add_f32_e32 v142, v152, v153
	v_add_f32_e32 v143, v44, v45
	ds_read_b128 v[76:79], v124 offset:9488
	v_add_f32_dpp v142, v142, v142 quad_perm:[1,0,3,2] row_mask:0xf bank_mask:0xf bound_ctrl:1
	v_add_f32_dpp v143, v143, v143 quad_perm:[1,0,3,2] row_mask:0xf bank_mask:0xf bound_ctrl:1
	ds_read_b128 v[72:75], v124 offset:9472
	v_add_f32_dpp v142, v142, v142 quad_perm:[2,3,0,1] row_mask:0xf bank_mask:0xf bound_ctrl:1
	v_add_f32_dpp v143, v143, v143 quad_perm:[2,3,0,1] row_mask:0xf bank_mask:0xf bound_ctrl:1
	ds_read_b128 v[68:71], v124 offset:9728
	v_add_f32_dpp v142, v142, v142 row_half_mirror row_mask:0xf bank_mask:0xf bound_ctrl:1
	v_add_f32_dpp v143, v143, v143 row_half_mirror row_mask:0xf bank_mask:0xf bound_ctrl:1
	ds_read_b128 v[56:59], v124 offset:9744
	ds_read2st64_b32 v[126:127], v135 offset0:41 offset1:47
	ds_read_b128 v[64:67], v124 offset:9984
	ds_read_b128 v[60:63], v124 offset:10000
	ds_read_b128 v[48:51], v124 offset:9216
	ds_read_b128 v[40:43], v124 offset:9232
	v_pk_mul_f32 v[182:183], v[182:183], v[142:143] op_sel_hi:[1,0]
	v_pk_mul_f32 v[184:185], v[184:185], v[142:143] op_sel_hi:[1,0]
	s_lshl_b64 vcc, vcc, 1
	v_pk_mul_f32 v[186:187], v[186:187], v[142:143] op_sel_hi:[1,0]
	v_pk_mul_f32 v[188:189], v[188:189], v[142:143] op_sel_hi:[1,0]
	v_pk_fma_f32 v[190:191], v[190:191], v[160:161], v[182:183] op_sel:[0,1,0] op_sel_hi:[1,1,1] neg_lo:[0,0,1] neg_hi:[0,0,1]
	v_pk_fma_f32 v[192:193], v[192:193], v[160:161], v[184:185] op_sel:[0,1,0] op_sel_hi:[1,1,1] neg_lo:[0,0,1] neg_hi:[0,0,1]
	v_cndmask_b32_e32 v134, v134, v143, vcc
	v_pk_fma_f32 v[194:195], v[194:195], v[160:161], v[186:187] op_sel:[0,1,0] op_sel_hi:[1,1,1] neg_lo:[0,0,1] neg_hi:[0,0,1]
	v_pk_fma_f32 v[196:197], v[196:197], v[160:161], v[188:189] op_sel:[0,1,0] op_sel_hi:[1,1,1] neg_lo:[0,0,1] neg_hi:[0,0,1]
	ds_read_b128 v[52:55], v124 offset:10256
	ds_read_b128 v[44:47], v124 offset:10240
	v_pk_fma_f32 v[36:37], v[36:37], v[144:145], v[190:191]
	v_pk_fma_f32 v[38:39], v[38:39], v[146:147], v[192:193]
	v_pk_fma_f32 v[32:33], v[32:33], v[148:149], v[194:195]
	v_pk_fma_f32 v[34:35], v[34:35], v[150:151], v[196:197]
	s_waitcnt lgkmcnt(2)
	v_pk_mul_f32 v[76:77], v[32:33], v[76:77]
	v_pk_mul_f32 v[202:203], v[32:33], v[202:203]
	v_pk_mul_f32 v[78:79], v[34:35], v[78:79]
	v_pk_mul_f32 v[204:205], v[34:35], v[204:205]
	v_pk_fma_f32 v[72:73], v[36:37], v[72:73], v[76:77]
	v_pk_fma_f32 v[198:199], v[36:37], v[198:199], v[202:203]
	v_pk_fma_f32 v[74:75], v[38:39], v[74:75], v[78:79]
	v_pk_fma_f32 v[200:201], v[38:39], v[200:201], v[204:205]
	v_pk_add_f32 v[72:73], v[72:73], v[74:75]
	v_pk_add_f32 v[198:199], v[198:199], v[200:201]
	v_add_f32_e32 v142, v72, v73
	v_add_f32_e32 v143, v198, v199
	ds_read_b128 v[156:159], v124 offset:11024
	v_add_f32_dpp v142, v142, v142 quad_perm:[1,0,3,2] row_mask:0xf bank_mask:0xf bound_ctrl:1
	v_add_f32_dpp v143, v143, v143 quad_perm:[1,0,3,2] row_mask:0xf bank_mask:0xf bound_ctrl:1
	ds_read_b128 v[152:155], v124 offset:11008
	v_add_f32_dpp v142, v142, v142 quad_perm:[2,3,0,1] row_mask:0xf bank_mask:0xf bound_ctrl:1
	v_add_f32_dpp v143, v143, v143 quad_perm:[2,3,0,1] row_mask:0xf bank_mask:0xf bound_ctrl:1
	ds_read_b128 v[182:185], v124 offset:11264
	v_add_f32_dpp v142, v142, v142 row_half_mirror row_mask:0xf bank_mask:0xf bound_ctrl:1
	v_add_f32_dpp v143, v143, v143 row_half_mirror row_mask:0xf bank_mask:0xf bound_ctrl:1
	ds_read_b128 v[186:189], v124 offset:11280
	ds_read_b128 v[190:193], v124 offset:11520
	ds_read_b128 v[194:197], v124 offset:11536
	ds_read_b128 v[144:147], v124 offset:10752
	ds_read_b128 v[148:151], v124 offset:10768
	v_pk_mul_f32 v[68:69], v[68:69], v[142:143] op_sel_hi:[1,0]
	v_pk_mul_f32 v[70:71], v[70:71], v[142:143] op_sel_hi:[1,0]
	s_lshl_b64 vcc, vcc, 1
	v_pk_mul_f32 v[56:57], v[56:57], v[142:143] op_sel_hi:[1,0]
	v_pk_mul_f32 v[58:59], v[58:59], v[142:143] op_sel_hi:[1,0]
	v_pk_fma_f32 v[64:65], v[64:65], v[126:127], v[68:69] op_sel_hi:[1,0,1] neg_lo:[0,0,1] neg_hi:[0,0,1]
	v_pk_fma_f32 v[66:67], v[66:67], v[126:127], v[70:71] op_sel_hi:[1,0,1] neg_lo:[0,0,1] neg_hi:[0,0,1]
	v_cndmask_b32_e32 v134, v134, v143, vcc
	v_pk_fma_f32 v[60:61], v[60:61], v[126:127], v[56:57] op_sel_hi:[1,0,1] neg_lo:[0,0,1] neg_hi:[0,0,1]
	v_pk_fma_f32 v[62:63], v[62:63], v[126:127], v[58:59] op_sel_hi:[1,0,1] neg_lo:[0,0,1] neg_hi:[0,0,1]
	ds_read_b128 v[202:205], v124 offset:11792
	ds_read_b128 v[198:201], v124 offset:11776
	v_pk_fma_f32 v[36:37], v[36:37], v[48:49], v[64:65]
	v_pk_fma_f32 v[38:39], v[38:39], v[50:51], v[66:67]
	v_pk_fma_f32 v[32:33], v[32:33], v[40:41], v[60:61]
	v_pk_fma_f32 v[34:35], v[34:35], v[42:43], v[62:63]
	s_waitcnt lgkmcnt(2)
	v_pk_mul_f32 v[156:157], v[32:33], v[156:157]
	v_pk_mul_f32 v[52:53], v[32:33], v[52:53]
	v_pk_mul_f32 v[158:159], v[34:35], v[158:159]
	v_pk_mul_f32 v[54:55], v[34:35], v[54:55]
	v_pk_fma_f32 v[152:153], v[36:37], v[152:153], v[156:157]
	v_pk_fma_f32 v[44:45], v[36:37], v[44:45], v[52:53]
	v_pk_fma_f32 v[154:155], v[38:39], v[154:155], v[158:159]
	v_pk_fma_f32 v[46:47], v[38:39], v[46:47], v[54:55]
	v_pk_add_f32 v[152:153], v[152:153], v[154:155]
	v_pk_add_f32 v[44:45], v[44:45], v[46:47]
	v_add_f32_e32 v142, v152, v153
	v_add_f32_e32 v143, v44, v45
	ds_read_b128 v[76:79], v124 offset:12560
	v_add_f32_dpp v142, v142, v142 quad_perm:[1,0,3,2] row_mask:0xf bank_mask:0xf bound_ctrl:1
	v_add_f32_dpp v143, v143, v143 quad_perm:[1,0,3,2] row_mask:0xf bank_mask:0xf bound_ctrl:1
	ds_read_b128 v[72:75], v124 offset:12544
	v_add_f32_dpp v142, v142, v142 quad_perm:[2,3,0,1] row_mask:0xf bank_mask:0xf bound_ctrl:1
	v_add_f32_dpp v143, v143, v143 quad_perm:[2,3,0,1] row_mask:0xf bank_mask:0xf bound_ctrl:1
	ds_read_b128 v[68:71], v124 offset:12800
	v_add_f32_dpp v142, v142, v142 row_half_mirror row_mask:0xf bank_mask:0xf bound_ctrl:1
	v_add_f32_dpp v143, v143, v143 row_half_mirror row_mask:0xf bank_mask:0xf bound_ctrl:1
	ds_read_b128 v[56:59], v124 offset:12816
	ds_read2st64_b32 v[160:161], v135 offset0:53 offset1:59
	ds_read_b128 v[64:67], v124 offset:13056
	ds_read_b128 v[60:63], v124 offset:13072
	ds_read_b128 v[48:51], v124 offset:12288
	ds_read_b128 v[40:43], v124 offset:12304
	v_pk_mul_f32 v[182:183], v[182:183], v[142:143] op_sel_hi:[1,0]
	v_pk_mul_f32 v[184:185], v[184:185], v[142:143] op_sel_hi:[1,0]
	s_lshl_b64 vcc, vcc, 1
	v_pk_mul_f32 v[186:187], v[186:187], v[142:143] op_sel_hi:[1,0]
	v_pk_mul_f32 v[188:189], v[188:189], v[142:143] op_sel_hi:[1,0]
	v_pk_fma_f32 v[190:191], v[190:191], v[126:127], v[182:183] op_sel:[0,1,0] op_sel_hi:[1,1,1] neg_lo:[0,0,1] neg_hi:[0,0,1]
	v_pk_fma_f32 v[192:193], v[192:193], v[126:127], v[184:185] op_sel:[0,1,0] op_sel_hi:[1,1,1] neg_lo:[0,0,1] neg_hi:[0,0,1]
	v_cndmask_b32_e32 v134, v134, v143, vcc
	v_pk_fma_f32 v[194:195], v[194:195], v[126:127], v[186:187] op_sel:[0,1,0] op_sel_hi:[1,1,1] neg_lo:[0,0,1] neg_hi:[0,0,1]
	v_pk_fma_f32 v[196:197], v[196:197], v[126:127], v[188:189] op_sel:[0,1,0] op_sel_hi:[1,1,1] neg_lo:[0,0,1] neg_hi:[0,0,1]
	ds_read_b128 v[52:55], v124 offset:13328
	ds_read_b128 v[44:47], v124 offset:13312
	v_pk_fma_f32 v[36:37], v[36:37], v[144:145], v[190:191]
	v_pk_fma_f32 v[38:39], v[38:39], v[146:147], v[192:193]
	v_pk_fma_f32 v[32:33], v[32:33], v[148:149], v[194:195]
	v_pk_fma_f32 v[34:35], v[34:35], v[150:151], v[196:197]
	s_waitcnt lgkmcnt(2)
	v_pk_mul_f32 v[76:77], v[32:33], v[76:77]
	v_pk_mul_f32 v[202:203], v[32:33], v[202:203]
	v_pk_mul_f32 v[78:79], v[34:35], v[78:79]
	v_pk_mul_f32 v[204:205], v[34:35], v[204:205]
	v_pk_fma_f32 v[72:73], v[36:37], v[72:73], v[76:77]
	v_pk_fma_f32 v[198:199], v[36:37], v[198:199], v[202:203]
	v_pk_fma_f32 v[74:75], v[38:39], v[74:75], v[78:79]
	v_pk_fma_f32 v[200:201], v[38:39], v[200:201], v[204:205]
	v_pk_add_f32 v[72:73], v[72:73], v[74:75]
	v_pk_add_f32 v[198:199], v[198:199], v[200:201]
	v_add_f32_e32 v142, v72, v73
	v_add_f32_e32 v143, v198, v199
	ds_read_b128 v[156:159], v124 offset:14096
	v_add_f32_dpp v142, v142, v142 quad_perm:[1,0,3,2] row_mask:0xf bank_mask:0xf bound_ctrl:1
	v_add_f32_dpp v143, v143, v143 quad_perm:[1,0,3,2] row_mask:0xf bank_mask:0xf bound_ctrl:1
	ds_read_b128 v[152:155], v124 offset:14080
	v_add_f32_dpp v142, v142, v142 quad_perm:[2,3,0,1] row_mask:0xf bank_mask:0xf bound_ctrl:1
	v_add_f32_dpp v143, v143, v143 quad_perm:[2,3,0,1] row_mask:0xf bank_mask:0xf bound_ctrl:1
	ds_read_b128 v[182:185], v124 offset:14336
	v_add_f32_dpp v142, v142, v142 row_half_mirror row_mask:0xf bank_mask:0xf bound_ctrl:1
	v_add_f32_dpp v143, v143, v143 row_half_mirror row_mask:0xf bank_mask:0xf bound_ctrl:1
	ds_read_b128 v[186:189], v124 offset:14352
	ds_read_b128 v[190:193], v124 offset:14592
	ds_read_b128 v[194:197], v124 offset:14608
	ds_read_b128 v[144:147], v124 offset:13824
	ds_read_b128 v[148:151], v124 offset:13840
	v_pk_mul_f32 v[68:69], v[68:69], v[142:143] op_sel_hi:[1,0]
	v_pk_mul_f32 v[70:71], v[70:71], v[142:143] op_sel_hi:[1,0]
	s_lshl_b64 vcc, vcc, 1
	v_pk_mul_f32 v[56:57], v[56:57], v[142:143] op_sel_hi:[1,0]
	v_pk_mul_f32 v[58:59], v[58:59], v[142:143] op_sel_hi:[1,0]
	v_pk_fma_f32 v[64:65], v[64:65], v[160:161], v[68:69] op_sel_hi:[1,0,1] neg_lo:[0,0,1] neg_hi:[0,0,1]
	v_pk_fma_f32 v[66:67], v[66:67], v[160:161], v[70:71] op_sel_hi:[1,0,1] neg_lo:[0,0,1] neg_hi:[0,0,1]
	v_cndmask_b32_e32 v134, v134, v143, vcc
	v_pk_fma_f32 v[60:61], v[60:61], v[160:161], v[56:57] op_sel_hi:[1,0,1] neg_lo:[0,0,1] neg_hi:[0,0,1]
	v_pk_fma_f32 v[62:63], v[62:63], v[160:161], v[58:59] op_sel_hi:[1,0,1] neg_lo:[0,0,1] neg_hi:[0,0,1]
	ds_read_b128 v[202:205], v124 offset:14864
	ds_read_b128 v[198:201], v124 offset:14848
	v_pk_fma_f32 v[36:37], v[36:37], v[48:49], v[64:65]
	v_pk_fma_f32 v[38:39], v[38:39], v[50:51], v[66:67]
	v_pk_fma_f32 v[32:33], v[32:33], v[40:41], v[60:61]
	v_pk_fma_f32 v[34:35], v[34:35], v[42:43], v[62:63]
	s_waitcnt lgkmcnt(2)
	v_pk_mul_f32 v[156:157], v[32:33], v[156:157]
	v_pk_mul_f32 v[52:53], v[32:33], v[52:53]
	v_pk_mul_f32 v[158:159], v[34:35], v[158:159]
	v_pk_mul_f32 v[54:55], v[34:35], v[54:55]
	v_pk_fma_f32 v[152:153], v[36:37], v[152:153], v[156:157]
	v_pk_fma_f32 v[44:45], v[36:37], v[44:45], v[52:53]
	v_pk_fma_f32 v[154:155], v[38:39], v[154:155], v[158:159]
	v_pk_fma_f32 v[46:47], v[38:39], v[46:47], v[54:55]
	v_pk_add_f32 v[152:153], v[152:153], v[154:155]
	v_pk_add_f32 v[44:45], v[44:45], v[46:47]
	v_add_f32_e32 v142, v152, v153
	v_add_f32_e32 v143, v44, v45
	ds_read_b128 v[76:79], v124 offset:15632
	v_add_f32_dpp v142, v142, v142 quad_perm:[1,0,3,2] row_mask:0xf bank_mask:0xf bound_ctrl:1
	v_add_f32_dpp v143, v143, v143 quad_perm:[1,0,3,2] row_mask:0xf bank_mask:0xf bound_ctrl:1
	ds_read_b128 v[72:75], v124 offset:15616
	v_add_f32_dpp v142, v142, v142 quad_perm:[2,3,0,1] row_mask:0xf bank_mask:0xf bound_ctrl:1
	v_add_f32_dpp v143, v143, v143 quad_perm:[2,3,0,1] row_mask:0xf bank_mask:0xf bound_ctrl:1
	ds_read_b128 v[68:71], v124 offset:15872
	v_add_f32_dpp v142, v142, v142 row_half_mirror row_mask:0xf bank_mask:0xf bound_ctrl:1
	v_add_f32_dpp v143, v143, v143 row_half_mirror row_mask:0xf bank_mask:0xf bound_ctrl:1
	ds_read_b128 v[56:59], v124 offset:15888
	ds_read2st64_b32 v[126:127], v135 offset0:65 offset1:71
	ds_read_b128 v[64:67], v124 offset:16128
	ds_read_b128 v[60:63], v124 offset:16144
	ds_read_b128 v[48:51], v124 offset:15360
	ds_read_b128 v[40:43], v124 offset:15376
	v_pk_mul_f32 v[182:183], v[182:183], v[142:143] op_sel_hi:[1,0]
	v_pk_mul_f32 v[184:185], v[184:185], v[142:143] op_sel_hi:[1,0]
	s_mov_b32 vcc_lo, 0x1010101
	v_pk_mul_f32 v[186:187], v[186:187], v[142:143] op_sel_hi:[1,0]
	v_pk_mul_f32 v[188:189], v[188:189], v[142:143] op_sel_hi:[1,0]
	s_mov_b32 vcc_hi, 0x1010101
	v_pk_fma_f32 v[190:191], v[190:191], v[160:161], v[182:183] op_sel:[0,1,0] op_sel_hi:[1,1,1] neg_lo:[0,0,1] neg_hi:[0,0,1]
	v_pk_fma_f32 v[192:193], v[192:193], v[160:161], v[184:185] op_sel:[0,1,0] op_sel_hi:[1,1,1] neg_lo:[0,0,1] neg_hi:[0,0,1]
	v_cndmask_b32_e32 v133, v133, v143, vcc
	v_pk_fma_f32 v[194:195], v[194:195], v[160:161], v[186:187] op_sel:[0,1,0] op_sel_hi:[1,1,1] neg_lo:[0,0,1] neg_hi:[0,0,1]
	v_pk_fma_f32 v[196:197], v[196:197], v[160:161], v[188:189] op_sel:[0,1,0] op_sel_hi:[1,1,1] neg_lo:[0,0,1] neg_hi:[0,0,1]
	ds_read_b128 v[52:55], v124 offset:16400
	ds_read_b128 v[44:47], v124 offset:16384
	v_pk_fma_f32 v[36:37], v[36:37], v[144:145], v[190:191]
	v_pk_fma_f32 v[38:39], v[38:39], v[146:147], v[192:193]
	v_pk_fma_f32 v[32:33], v[32:33], v[148:149], v[194:195]
	v_pk_fma_f32 v[34:35], v[34:35], v[150:151], v[196:197]
	s_waitcnt lgkmcnt(2)
	v_pk_mul_f32 v[76:77], v[32:33], v[76:77]
	v_pk_mul_f32 v[202:203], v[32:33], v[202:203]
	v_pk_mul_f32 v[78:79], v[34:35], v[78:79]
	v_pk_mul_f32 v[204:205], v[34:35], v[204:205]
	v_pk_fma_f32 v[72:73], v[36:37], v[72:73], v[76:77]
	v_pk_fma_f32 v[198:199], v[36:37], v[198:199], v[202:203]
	v_pk_fma_f32 v[74:75], v[38:39], v[74:75], v[78:79]
	v_pk_fma_f32 v[200:201], v[38:39], v[200:201], v[204:205]
	v_pk_add_f32 v[72:73], v[72:73], v[74:75]
	v_pk_add_f32 v[198:199], v[198:199], v[200:201]
	v_add_f32_e32 v142, v72, v73
	v_add_f32_e32 v143, v198, v199
	ds_read_b128 v[156:159], v124 offset:17168
	v_add_f32_dpp v142, v142, v142 quad_perm:[1,0,3,2] row_mask:0xf bank_mask:0xf bound_ctrl:1
	v_add_f32_dpp v143, v143, v143 quad_perm:[1,0,3,2] row_mask:0xf bank_mask:0xf bound_ctrl:1
	ds_read_b128 v[152:155], v124 offset:17152
	v_add_f32_dpp v142, v142, v142 quad_perm:[2,3,0,1] row_mask:0xf bank_mask:0xf bound_ctrl:1
	v_add_f32_dpp v143, v143, v143 quad_perm:[2,3,0,1] row_mask:0xf bank_mask:0xf bound_ctrl:1
	ds_read_b128 v[182:185], v124 offset:17408
	v_add_f32_dpp v142, v142, v142 row_half_mirror row_mask:0xf bank_mask:0xf bound_ctrl:1
	v_add_f32_dpp v143, v143, v143 row_half_mirror row_mask:0xf bank_mask:0xf bound_ctrl:1
	ds_read_b128 v[186:189], v124 offset:17424
	ds_read_b128 v[190:193], v124 offset:17664
	ds_read_b128 v[194:197], v124 offset:17680
	ds_read_b128 v[144:147], v124 offset:16896
	ds_read_b128 v[148:151], v124 offset:16912
	v_pk_mul_f32 v[68:69], v[68:69], v[142:143] op_sel_hi:[1,0]
	v_pk_mul_f32 v[70:71], v[70:71], v[142:143] op_sel_hi:[1,0]
	s_lshl_b64 vcc, vcc, 1
	v_pk_mul_f32 v[56:57], v[56:57], v[142:143] op_sel_hi:[1,0]
	v_pk_mul_f32 v[58:59], v[58:59], v[142:143] op_sel_hi:[1,0]
	v_pk_fma_f32 v[64:65], v[64:65], v[126:127], v[68:69] op_sel_hi:[1,0,1] neg_lo:[0,0,1] neg_hi:[0,0,1]
	v_pk_fma_f32 v[66:67], v[66:67], v[126:127], v[70:71] op_sel_hi:[1,0,1] neg_lo:[0,0,1] neg_hi:[0,0,1]
	v_cndmask_b32_e32 v133, v133, v143, vcc
	v_pk_fma_f32 v[60:61], v[60:61], v[126:127], v[56:57] op_sel_hi:[1,0,1] neg_lo:[0,0,1] neg_hi:[0,0,1]
	v_pk_fma_f32 v[62:63], v[62:63], v[126:127], v[58:59] op_sel_hi:[1,0,1] neg_lo:[0,0,1] neg_hi:[0,0,1]
	ds_read_b128 v[202:205], v124 offset:17936
	ds_read_b128 v[198:201], v124 offset:17920
	v_pk_fma_f32 v[36:37], v[36:37], v[48:49], v[64:65]
	v_pk_fma_f32 v[38:39], v[38:39], v[50:51], v[66:67]
	v_pk_fma_f32 v[32:33], v[32:33], v[40:41], v[60:61]
	v_pk_fma_f32 v[34:35], v[34:35], v[42:43], v[62:63]
	s_waitcnt lgkmcnt(2)
	v_pk_mul_f32 v[156:157], v[32:33], v[156:157]
	v_pk_mul_f32 v[52:53], v[32:33], v[52:53]
	v_pk_mul_f32 v[158:159], v[34:35], v[158:159]
	v_pk_mul_f32 v[54:55], v[34:35], v[54:55]
	v_pk_fma_f32 v[152:153], v[36:37], v[152:153], v[156:157]
	v_pk_fma_f32 v[44:45], v[36:37], v[44:45], v[52:53]
	v_pk_fma_f32 v[154:155], v[38:39], v[154:155], v[158:159]
	v_pk_fma_f32 v[46:47], v[38:39], v[46:47], v[54:55]
	v_pk_add_f32 v[152:153], v[152:153], v[154:155]
	v_pk_add_f32 v[44:45], v[44:45], v[46:47]
	v_add_f32_e32 v142, v152, v153
	v_add_f32_e32 v143, v44, v45
	ds_read_b128 v[76:79], v124 offset:18704
	v_add_f32_dpp v142, v142, v142 quad_perm:[1,0,3,2] row_mask:0xf bank_mask:0xf bound_ctrl:1
	v_add_f32_dpp v143, v143, v143 quad_perm:[1,0,3,2] row_mask:0xf bank_mask:0xf bound_ctrl:1
	ds_read_b128 v[72:75], v124 offset:18688
	v_add_f32_dpp v142, v142, v142 quad_perm:[2,3,0,1] row_mask:0xf bank_mask:0xf bound_ctrl:1
	v_add_f32_dpp v143, v143, v143 quad_perm:[2,3,0,1] row_mask:0xf bank_mask:0xf bound_ctrl:1
	ds_read_b128 v[68:71], v124 offset:18944
	v_add_f32_dpp v142, v142, v142 row_half_mirror row_mask:0xf bank_mask:0xf bound_ctrl:1
	v_add_f32_dpp v143, v143, v143 row_half_mirror row_mask:0xf bank_mask:0xf bound_ctrl:1
	ds_read_b128 v[56:59], v124 offset:18960
	ds_read2st64_b32 v[160:161], v135 offset0:77 offset1:83
	ds_read_b128 v[64:67], v124 offset:19200
	ds_read_b128 v[60:63], v124 offset:19216
	ds_read_b128 v[48:51], v124 offset:18432
	ds_read_b128 v[40:43], v124 offset:18448
	v_pk_mul_f32 v[182:183], v[182:183], v[142:143] op_sel_hi:[1,0]
	v_pk_mul_f32 v[184:185], v[184:185], v[142:143] op_sel_hi:[1,0]
	s_lshl_b64 vcc, vcc, 1
	v_pk_mul_f32 v[186:187], v[186:187], v[142:143] op_sel_hi:[1,0]
	v_pk_mul_f32 v[188:189], v[188:189], v[142:143] op_sel_hi:[1,0]
	v_pk_fma_f32 v[190:191], v[190:191], v[126:127], v[182:183] op_sel:[0,1,0] op_sel_hi:[1,1,1] neg_lo:[0,0,1] neg_hi:[0,0,1]
	v_pk_fma_f32 v[192:193], v[192:193], v[126:127], v[184:185] op_sel:[0,1,0] op_sel_hi:[1,1,1] neg_lo:[0,0,1] neg_hi:[0,0,1]
	v_cndmask_b32_e32 v133, v133, v143, vcc
	v_pk_fma_f32 v[194:195], v[194:195], v[126:127], v[186:187] op_sel:[0,1,0] op_sel_hi:[1,1,1] neg_lo:[0,0,1] neg_hi:[0,0,1]
	v_pk_fma_f32 v[196:197], v[196:197], v[126:127], v[188:189] op_sel:[0,1,0] op_sel_hi:[1,1,1] neg_lo:[0,0,1] neg_hi:[0,0,1]
	ds_read_b128 v[52:55], v124 offset:19472
	ds_read_b128 v[44:47], v124 offset:19456
	v_pk_fma_f32 v[36:37], v[36:37], v[144:145], v[190:191]
	v_pk_fma_f32 v[38:39], v[38:39], v[146:147], v[192:193]
	v_pk_fma_f32 v[32:33], v[32:33], v[148:149], v[194:195]
	v_pk_fma_f32 v[34:35], v[34:35], v[150:151], v[196:197]
	s_waitcnt lgkmcnt(2)
	v_pk_mul_f32 v[76:77], v[32:33], v[76:77]
	v_pk_mul_f32 v[202:203], v[32:33], v[202:203]
	v_pk_mul_f32 v[78:79], v[34:35], v[78:79]
	v_pk_mul_f32 v[204:205], v[34:35], v[204:205]
	v_pk_fma_f32 v[72:73], v[36:37], v[72:73], v[76:77]
	v_pk_fma_f32 v[198:199], v[36:37], v[198:199], v[202:203]
	v_pk_fma_f32 v[74:75], v[38:39], v[74:75], v[78:79]
	v_pk_fma_f32 v[200:201], v[38:39], v[200:201], v[204:205]
	v_pk_add_f32 v[72:73], v[72:73], v[74:75]
	v_pk_add_f32 v[198:199], v[198:199], v[200:201]
	v_add_f32_e32 v142, v72, v73
	v_add_f32_e32 v143, v198, v199
	ds_read_b128 v[156:159], v124 offset:20240
	v_add_f32_dpp v142, v142, v142 quad_perm:[1,0,3,2] row_mask:0xf bank_mask:0xf bound_ctrl:1
	v_add_f32_dpp v143, v143, v143 quad_perm:[1,0,3,2] row_mask:0xf bank_mask:0xf bound_ctrl:1
	ds_read_b128 v[152:155], v124 offset:20224
	v_add_f32_dpp v142, v142, v142 quad_perm:[2,3,0,1] row_mask:0xf bank_mask:0xf bound_ctrl:1
	v_add_f32_dpp v143, v143, v143 quad_perm:[2,3,0,1] row_mask:0xf bank_mask:0xf bound_ctrl:1
	ds_read_b128 v[182:185], v124 offset:20480
	v_add_f32_dpp v142, v142, v142 row_half_mirror row_mask:0xf bank_mask:0xf bound_ctrl:1
	v_add_f32_dpp v143, v143, v143 row_half_mirror row_mask:0xf bank_mask:0xf bound_ctrl:1
	ds_read_b128 v[186:189], v124 offset:20496
	ds_read_b128 v[190:193], v124 offset:20736
	ds_read_b128 v[194:197], v124 offset:20752
	ds_read_b128 v[144:147], v124 offset:19968
	ds_read_b128 v[148:151], v124 offset:19984
	v_pk_mul_f32 v[68:69], v[68:69], v[142:143] op_sel_hi:[1,0]
	v_pk_mul_f32 v[70:71], v[70:71], v[142:143] op_sel_hi:[1,0]
	s_lshl_b64 vcc, vcc, 1
	v_pk_mul_f32 v[56:57], v[56:57], v[142:143] op_sel_hi:[1,0]
	v_pk_mul_f32 v[58:59], v[58:59], v[142:143] op_sel_hi:[1,0]
	v_pk_fma_f32 v[64:65], v[64:65], v[160:161], v[68:69] op_sel_hi:[1,0,1] neg_lo:[0,0,1] neg_hi:[0,0,1]
	v_pk_fma_f32 v[66:67], v[66:67], v[160:161], v[70:71] op_sel_hi:[1,0,1] neg_lo:[0,0,1] neg_hi:[0,0,1]
	v_cndmask_b32_e32 v133, v133, v143, vcc
	v_pk_fma_f32 v[60:61], v[60:61], v[160:161], v[56:57] op_sel_hi:[1,0,1] neg_lo:[0,0,1] neg_hi:[0,0,1]
	v_pk_fma_f32 v[62:63], v[62:63], v[160:161], v[58:59] op_sel_hi:[1,0,1] neg_lo:[0,0,1] neg_hi:[0,0,1]
	ds_read_b128 v[202:205], v124 offset:21008
	ds_read_b128 v[198:201], v124 offset:20992
	v_pk_fma_f32 v[36:37], v[36:37], v[48:49], v[64:65]
	v_pk_fma_f32 v[38:39], v[38:39], v[50:51], v[66:67]
	v_pk_fma_f32 v[32:33], v[32:33], v[40:41], v[60:61]
	v_pk_fma_f32 v[34:35], v[34:35], v[42:43], v[62:63]
	s_waitcnt lgkmcnt(2)
	v_pk_mul_f32 v[156:157], v[32:33], v[156:157]
	v_pk_mul_f32 v[52:53], v[32:33], v[52:53]
	v_pk_mul_f32 v[158:159], v[34:35], v[158:159]
	v_pk_mul_f32 v[54:55], v[34:35], v[54:55]
	v_pk_fma_f32 v[152:153], v[36:37], v[152:153], v[156:157]
	v_pk_fma_f32 v[44:45], v[36:37], v[44:45], v[52:53]
	v_pk_fma_f32 v[154:155], v[38:39], v[154:155], v[158:159]
	v_pk_fma_f32 v[46:47], v[38:39], v[46:47], v[54:55]
	v_pk_add_f32 v[152:153], v[152:153], v[154:155]
	v_pk_add_f32 v[44:45], v[44:45], v[46:47]
	v_add_f32_e32 v142, v152, v153
	v_add_f32_e32 v143, v44, v45
	ds_read_b128 v[76:79], v124 offset:21776
	v_add_f32_dpp v142, v142, v142 quad_perm:[1,0,3,2] row_mask:0xf bank_mask:0xf bound_ctrl:1
	v_add_f32_dpp v143, v143, v143 quad_perm:[1,0,3,2] row_mask:0xf bank_mask:0xf bound_ctrl:1
	ds_read_b128 v[72:75], v124 offset:21760
	v_add_f32_dpp v142, v142, v142 quad_perm:[2,3,0,1] row_mask:0xf bank_mask:0xf bound_ctrl:1
	v_add_f32_dpp v143, v143, v143 quad_perm:[2,3,0,1] row_mask:0xf bank_mask:0xf bound_ctrl:1
	ds_read_b128 v[68:71], v124 offset:22016
	v_add_f32_dpp v142, v142, v142 row_half_mirror row_mask:0xf bank_mask:0xf bound_ctrl:1
	v_add_f32_dpp v143, v143, v143 row_half_mirror row_mask:0xf bank_mask:0xf bound_ctrl:1
	ds_read_b128 v[56:59], v124 offset:22032
	ds_read2st64_b32 v[126:127], v135 offset0:89 offset1:95
	ds_read_b128 v[64:67], v124 offset:22272
	ds_read_b128 v[60:63], v124 offset:22288
	ds_read_b128 v[48:51], v124 offset:21504
	ds_read_b128 v[40:43], v124 offset:21520
	v_pk_mul_f32 v[182:183], v[182:183], v[142:143] op_sel_hi:[1,0]
	v_pk_mul_f32 v[184:185], v[184:185], v[142:143] op_sel_hi:[1,0]
	s_lshl_b64 vcc, vcc, 1
	v_pk_mul_f32 v[186:187], v[186:187], v[142:143] op_sel_hi:[1,0]
	v_pk_mul_f32 v[188:189], v[188:189], v[142:143] op_sel_hi:[1,0]
	v_pk_fma_f32 v[190:191], v[190:191], v[160:161], v[182:183] op_sel:[0,1,0] op_sel_hi:[1,1,1] neg_lo:[0,0,1] neg_hi:[0,0,1]
	v_pk_fma_f32 v[192:193], v[192:193], v[160:161], v[184:185] op_sel:[0,1,0] op_sel_hi:[1,1,1] neg_lo:[0,0,1] neg_hi:[0,0,1]
	v_cndmask_b32_e32 v133, v133, v143, vcc
	v_pk_fma_f32 v[194:195], v[194:195], v[160:161], v[186:187] op_sel:[0,1,0] op_sel_hi:[1,1,1] neg_lo:[0,0,1] neg_hi:[0,0,1]
	v_pk_fma_f32 v[196:197], v[196:197], v[160:161], v[188:189] op_sel:[0,1,0] op_sel_hi:[1,1,1] neg_lo:[0,0,1] neg_hi:[0,0,1]
	ds_read_b128 v[52:55], v124 offset:22544
	ds_read_b128 v[44:47], v124 offset:22528
	v_pk_fma_f32 v[36:37], v[36:37], v[144:145], v[190:191]
	v_pk_fma_f32 v[38:39], v[38:39], v[146:147], v[192:193]
	v_pk_fma_f32 v[32:33], v[32:33], v[148:149], v[194:195]
	v_pk_fma_f32 v[34:35], v[34:35], v[150:151], v[196:197]
	s_waitcnt lgkmcnt(2)
	v_pk_mul_f32 v[76:77], v[32:33], v[76:77]
	v_pk_mul_f32 v[202:203], v[32:33], v[202:203]
	v_pk_mul_f32 v[78:79], v[34:35], v[78:79]
	v_pk_mul_f32 v[204:205], v[34:35], v[204:205]
	v_pk_fma_f32 v[72:73], v[36:37], v[72:73], v[76:77]
	v_pk_fma_f32 v[198:199], v[36:37], v[198:199], v[202:203]
	v_pk_fma_f32 v[74:75], v[38:39], v[74:75], v[78:79]
	v_pk_fma_f32 v[200:201], v[38:39], v[200:201], v[204:205]
	v_pk_add_f32 v[72:73], v[72:73], v[74:75]
	v_pk_add_f32 v[198:199], v[198:199], v[200:201]
	v_add_f32_e32 v142, v72, v73
	v_add_f32_e32 v143, v198, v199
	ds_read_b128 v[156:159], v124 offset:23312
	v_add_f32_dpp v142, v142, v142 quad_perm:[1,0,3,2] row_mask:0xf bank_mask:0xf bound_ctrl:1
	v_add_f32_dpp v143, v143, v143 quad_perm:[1,0,3,2] row_mask:0xf bank_mask:0xf bound_ctrl:1
	ds_read_b128 v[152:155], v124 offset:23296
	v_add_f32_dpp v142, v142, v142 quad_perm:[2,3,0,1] row_mask:0xf bank_mask:0xf bound_ctrl:1
	v_add_f32_dpp v143, v143, v143 quad_perm:[2,3,0,1] row_mask:0xf bank_mask:0xf bound_ctrl:1
	ds_read_b128 v[182:185], v124 offset:23552
	v_add_f32_dpp v142, v142, v142 row_half_mirror row_mask:0xf bank_mask:0xf bound_ctrl:1
	v_add_f32_dpp v143, v143, v143 row_half_mirror row_mask:0xf bank_mask:0xf bound_ctrl:1
	ds_read_b128 v[186:189], v124 offset:23568
	ds_read_b128 v[190:193], v124 offset:23808
	ds_read_b128 v[194:197], v124 offset:23824
	ds_read_b128 v[144:147], v124 offset:23040
	ds_read_b128 v[148:151], v124 offset:23056
	v_pk_mul_f32 v[68:69], v[68:69], v[142:143] op_sel_hi:[1,0]
	v_pk_mul_f32 v[70:71], v[70:71], v[142:143] op_sel_hi:[1,0]
	s_lshl_b64 vcc, vcc, 1
	v_pk_mul_f32 v[56:57], v[56:57], v[142:143] op_sel_hi:[1,0]
	v_pk_mul_f32 v[58:59], v[58:59], v[142:143] op_sel_hi:[1,0]
	v_pk_fma_f32 v[64:65], v[64:65], v[126:127], v[68:69] op_sel_hi:[1,0,1] neg_lo:[0,0,1] neg_hi:[0,0,1]
	v_pk_fma_f32 v[66:67], v[66:67], v[126:127], v[70:71] op_sel_hi:[1,0,1] neg_lo:[0,0,1] neg_hi:[0,0,1]
	v_cndmask_b32_e32 v133, v133, v143, vcc
	v_pk_fma_f32 v[60:61], v[60:61], v[126:127], v[56:57] op_sel_hi:[1,0,1] neg_lo:[0,0,1] neg_hi:[0,0,1]
	v_pk_fma_f32 v[62:63], v[62:63], v[126:127], v[58:59] op_sel_hi:[1,0,1] neg_lo:[0,0,1] neg_hi:[0,0,1]
	ds_read_b128 v[202:205], v124 offset:24080
	ds_read_b128 v[198:201], v124 offset:24064
	v_pk_fma_f32 v[36:37], v[36:37], v[48:49], v[64:65]
	v_pk_fma_f32 v[38:39], v[38:39], v[50:51], v[66:67]
	v_pk_fma_f32 v[32:33], v[32:33], v[40:41], v[60:61]
	v_pk_fma_f32 v[34:35], v[34:35], v[42:43], v[62:63]
	s_waitcnt lgkmcnt(2)
	v_pk_mul_f32 v[156:157], v[32:33], v[156:157]
	v_pk_mul_f32 v[52:53], v[32:33], v[52:53]
	v_pk_mul_f32 v[158:159], v[34:35], v[158:159]
	v_pk_mul_f32 v[54:55], v[34:35], v[54:55]
	v_pk_fma_f32 v[152:153], v[36:37], v[152:153], v[156:157]
	v_pk_fma_f32 v[44:45], v[36:37], v[44:45], v[52:53]
	v_pk_fma_f32 v[154:155], v[38:39], v[154:155], v[158:159]
	v_pk_fma_f32 v[46:47], v[38:39], v[46:47], v[54:55]
	v_pk_add_f32 v[152:153], v[152:153], v[154:155]
	v_pk_add_f32 v[44:45], v[44:45], v[46:47]
	v_add_f32_e32 v142, v152, v153
	v_add_f32_e32 v143, v44, v45
	ds_read_b128 v[76:79], v124 offset:24848
	v_add_f32_dpp v142, v142, v142 quad_perm:[1,0,3,2] row_mask:0xf bank_mask:0xf bound_ctrl:1
	v_add_f32_dpp v143, v143, v143 quad_perm:[1,0,3,2] row_mask:0xf bank_mask:0xf bound_ctrl:1
	ds_read_b128 v[72:75], v124 offset:24832
	v_add_f32_dpp v142, v142, v142 quad_perm:[2,3,0,1] row_mask:0xf bank_mask:0xf bound_ctrl:1
	v_add_f32_dpp v143, v143, v143 quad_perm:[2,3,0,1] row_mask:0xf bank_mask:0xf bound_ctrl:1
	ds_read_b128 v[68:71], v124 offset:25088
	v_add_f32_dpp v142, v142, v142 row_half_mirror row_mask:0xf bank_mask:0xf bound_ctrl:1
	v_add_f32_dpp v143, v143, v143 row_half_mirror row_mask:0xf bank_mask:0xf bound_ctrl:1
	ds_read_b128 v[56:59], v124 offset:25104
	ds_read2st64_b32 v[160:161], v135 offset0:101 offset1:107
	ds_read_b128 v[64:67], v124 offset:25344
	ds_read_b128 v[60:63], v124 offset:25360
	ds_read_b128 v[48:51], v124 offset:24576
	ds_read_b128 v[40:43], v124 offset:24592
	v_pk_mul_f32 v[182:183], v[182:183], v[142:143] op_sel_hi:[1,0]
	v_pk_mul_f32 v[184:185], v[184:185], v[142:143] op_sel_hi:[1,0]
	s_lshl_b64 vcc, vcc, 1
	v_pk_mul_f32 v[186:187], v[186:187], v[142:143] op_sel_hi:[1,0]
	v_pk_mul_f32 v[188:189], v[188:189], v[142:143] op_sel_hi:[1,0]
	v_pk_fma_f32 v[190:191], v[190:191], v[126:127], v[182:183] op_sel:[0,1,0] op_sel_hi:[1,1,1] neg_lo:[0,0,1] neg_hi:[0,0,1]
	v_pk_fma_f32 v[192:193], v[192:193], v[126:127], v[184:185] op_sel:[0,1,0] op_sel_hi:[1,1,1] neg_lo:[0,0,1] neg_hi:[0,0,1]
	v_cndmask_b32_e32 v133, v133, v143, vcc
	v_pk_fma_f32 v[194:195], v[194:195], v[126:127], v[186:187] op_sel:[0,1,0] op_sel_hi:[1,1,1] neg_lo:[0,0,1] neg_hi:[0,0,1]
	v_pk_fma_f32 v[196:197], v[196:197], v[126:127], v[188:189] op_sel:[0,1,0] op_sel_hi:[1,1,1] neg_lo:[0,0,1] neg_hi:[0,0,1]
	ds_read_b128 v[52:55], v124 offset:25616
	ds_read_b128 v[44:47], v124 offset:25600
	v_pk_fma_f32 v[36:37], v[36:37], v[144:145], v[190:191]
	v_pk_fma_f32 v[38:39], v[38:39], v[146:147], v[192:193]
	v_pk_fma_f32 v[32:33], v[32:33], v[148:149], v[194:195]
	v_pk_fma_f32 v[34:35], v[34:35], v[150:151], v[196:197]
	s_waitcnt lgkmcnt(2)
	v_pk_mul_f32 v[76:77], v[32:33], v[76:77]
	v_pk_mul_f32 v[202:203], v[32:33], v[202:203]
	v_pk_mul_f32 v[78:79], v[34:35], v[78:79]
	v_pk_mul_f32 v[204:205], v[34:35], v[204:205]
	v_pk_fma_f32 v[72:73], v[36:37], v[72:73], v[76:77]
	v_pk_fma_f32 v[198:199], v[36:37], v[198:199], v[202:203]
	v_pk_fma_f32 v[74:75], v[38:39], v[74:75], v[78:79]
	v_pk_fma_f32 v[200:201], v[38:39], v[200:201], v[204:205]
	v_pk_add_f32 v[72:73], v[72:73], v[74:75]
	v_pk_add_f32 v[198:199], v[198:199], v[200:201]
	v_add_f32_e32 v142, v72, v73
	v_add_f32_e32 v143, v198, v199
	ds_read_b128 v[156:159], v124 offset:26384
	v_add_f32_dpp v142, v142, v142 quad_perm:[1,0,3,2] row_mask:0xf bank_mask:0xf bound_ctrl:1
	v_add_f32_dpp v143, v143, v143 quad_perm:[1,0,3,2] row_mask:0xf bank_mask:0xf bound_ctrl:1
	ds_read_b128 v[152:155], v124 offset:26368
	v_add_f32_dpp v142, v142, v142 quad_perm:[2,3,0,1] row_mask:0xf bank_mask:0xf bound_ctrl:1
	v_add_f32_dpp v143, v143, v143 quad_perm:[2,3,0,1] row_mask:0xf bank_mask:0xf bound_ctrl:1
	ds_read_b128 v[182:185], v124 offset:26624
	v_add_f32_dpp v142, v142, v142 row_half_mirror row_mask:0xf bank_mask:0xf bound_ctrl:1
	v_add_f32_dpp v143, v143, v143 row_half_mirror row_mask:0xf bank_mask:0xf bound_ctrl:1
	ds_read_b128 v[186:189], v124 offset:26640
	ds_read_b128 v[190:193], v124 offset:26880
	ds_read_b128 v[194:197], v124 offset:26896
	ds_read_b128 v[144:147], v124 offset:26112
	ds_read_b128 v[148:151], v124 offset:26128
	v_pk_mul_f32 v[68:69], v[68:69], v[142:143] op_sel_hi:[1,0]
	v_pk_mul_f32 v[70:71], v[70:71], v[142:143] op_sel_hi:[1,0]
	s_lshl_b64 vcc, vcc, 1
	v_pk_mul_f32 v[56:57], v[56:57], v[142:143] op_sel_hi:[1,0]
	v_pk_mul_f32 v[58:59], v[58:59], v[142:143] op_sel_hi:[1,0]
	v_pk_fma_f32 v[64:65], v[64:65], v[160:161], v[68:69] op_sel_hi:[1,0,1] neg_lo:[0,0,1] neg_hi:[0,0,1]
	v_pk_fma_f32 v[66:67], v[66:67], v[160:161], v[70:71] op_sel_hi:[1,0,1] neg_lo:[0,0,1] neg_hi:[0,0,1]
	v_cndmask_b32_e32 v133, v133, v143, vcc
	v_pk_fma_f32 v[60:61], v[60:61], v[160:161], v[56:57] op_sel_hi:[1,0,1] neg_lo:[0,0,1] neg_hi:[0,0,1]
	v_pk_fma_f32 v[62:63], v[62:63], v[160:161], v[58:59] op_sel_hi:[1,0,1] neg_lo:[0,0,1] neg_hi:[0,0,1]
	ds_read_b128 v[202:205], v124 offset:27152
	ds_read_b128 v[198:201], v124 offset:27136
	v_pk_fma_f32 v[36:37], v[36:37], v[48:49], v[64:65]
	v_pk_fma_f32 v[38:39], v[38:39], v[50:51], v[66:67]
	v_pk_fma_f32 v[32:33], v[32:33], v[40:41], v[60:61]
	v_pk_fma_f32 v[34:35], v[34:35], v[42:43], v[62:63]
	s_waitcnt lgkmcnt(2)
	v_pk_mul_f32 v[156:157], v[32:33], v[156:157]
	v_pk_mul_f32 v[52:53], v[32:33], v[52:53]
	v_pk_mul_f32 v[158:159], v[34:35], v[158:159]
	v_pk_mul_f32 v[54:55], v[34:35], v[54:55]
	v_pk_fma_f32 v[152:153], v[36:37], v[152:153], v[156:157]
	v_pk_fma_f32 v[44:45], v[36:37], v[44:45], v[52:53]
	v_pk_fma_f32 v[154:155], v[38:39], v[154:155], v[158:159]
	v_pk_fma_f32 v[46:47], v[38:39], v[46:47], v[54:55]
	v_pk_add_f32 v[152:153], v[152:153], v[154:155]
	v_pk_add_f32 v[44:45], v[44:45], v[46:47]
	v_add_f32_e32 v142, v152, v153
	v_add_f32_e32 v143, v44, v45
	ds_read_b128 v[76:79], v124 offset:27920
	v_add_f32_dpp v142, v142, v142 quad_perm:[1,0,3,2] row_mask:0xf bank_mask:0xf bound_ctrl:1
	v_add_f32_dpp v143, v143, v143 quad_perm:[1,0,3,2] row_mask:0xf bank_mask:0xf bound_ctrl:1
	ds_read_b128 v[72:75], v124 offset:27904
	v_add_f32_dpp v142, v142, v142 quad_perm:[2,3,0,1] row_mask:0xf bank_mask:0xf bound_ctrl:1
	v_add_f32_dpp v143, v143, v143 quad_perm:[2,3,0,1] row_mask:0xf bank_mask:0xf bound_ctrl:1
	ds_read_b128 v[68:71], v124 offset:28160
	v_add_f32_dpp v142, v142, v142 row_half_mirror row_mask:0xf bank_mask:0xf bound_ctrl:1
	v_add_f32_dpp v143, v143, v143 row_half_mirror row_mask:0xf bank_mask:0xf bound_ctrl:1
	ds_read_b128 v[56:59], v124 offset:28176
	ds_read2st64_b32 v[126:127], v135 offset0:113 offset1:119
	ds_read_b128 v[64:67], v124 offset:28416
	ds_read_b128 v[60:63], v124 offset:28432
	ds_read_b128 v[48:51], v124 offset:27648
	ds_read_b128 v[40:43], v124 offset:27664
	v_pk_mul_f32 v[182:183], v[182:183], v[142:143] op_sel_hi:[1,0]
	v_pk_mul_f32 v[184:185], v[184:185], v[142:143] op_sel_hi:[1,0]
	s_mov_b32 vcc_lo, 0x1010101
	v_pk_mul_f32 v[186:187], v[186:187], v[142:143] op_sel_hi:[1,0]
	v_pk_mul_f32 v[188:189], v[188:189], v[142:143] op_sel_hi:[1,0]
	s_mov_b32 vcc_hi, 0x1010101
	v_pk_fma_f32 v[190:191], v[190:191], v[160:161], v[182:183] op_sel:[0,1,0] op_sel_hi:[1,1,1] neg_lo:[0,0,1] neg_hi:[0,0,1]
	v_pk_fma_f32 v[192:193], v[192:193], v[160:161], v[184:185] op_sel:[0,1,0] op_sel_hi:[1,1,1] neg_lo:[0,0,1] neg_hi:[0,0,1]
	v_cndmask_b32_e32 v132, v132, v143, vcc
	v_pk_fma_f32 v[194:195], v[194:195], v[160:161], v[186:187] op_sel:[0,1,0] op_sel_hi:[1,1,1] neg_lo:[0,0,1] neg_hi:[0,0,1]
	v_pk_fma_f32 v[196:197], v[196:197], v[160:161], v[188:189] op_sel:[0,1,0] op_sel_hi:[1,1,1] neg_lo:[0,0,1] neg_hi:[0,0,1]
	ds_read_b128 v[52:55], v124 offset:28688
	ds_read_b128 v[44:47], v124 offset:28672
	v_pk_fma_f32 v[36:37], v[36:37], v[144:145], v[190:191]
	v_pk_fma_f32 v[38:39], v[38:39], v[146:147], v[192:193]
	v_pk_fma_f32 v[32:33], v[32:33], v[148:149], v[194:195]
	v_pk_fma_f32 v[34:35], v[34:35], v[150:151], v[196:197]
	s_waitcnt lgkmcnt(2)
	v_pk_mul_f32 v[76:77], v[32:33], v[76:77]
	v_pk_mul_f32 v[202:203], v[32:33], v[202:203]
	v_pk_mul_f32 v[78:79], v[34:35], v[78:79]
	v_pk_mul_f32 v[204:205], v[34:35], v[204:205]
	v_pk_fma_f32 v[72:73], v[36:37], v[72:73], v[76:77]
	v_pk_fma_f32 v[198:199], v[36:37], v[198:199], v[202:203]
	v_pk_fma_f32 v[74:75], v[38:39], v[74:75], v[78:79]
	v_pk_fma_f32 v[200:201], v[38:39], v[200:201], v[204:205]
	v_pk_add_f32 v[72:73], v[72:73], v[74:75]
	v_pk_add_f32 v[198:199], v[198:199], v[200:201]
	v_add_f32_e32 v142, v72, v73
	v_add_f32_e32 v143, v198, v199
	ds_read_b128 v[156:159], v124 offset:29456
	v_add_f32_dpp v142, v142, v142 quad_perm:[1,0,3,2] row_mask:0xf bank_mask:0xf bound_ctrl:1
	v_add_f32_dpp v143, v143, v143 quad_perm:[1,0,3,2] row_mask:0xf bank_mask:0xf bound_ctrl:1
	ds_read_b128 v[152:155], v124 offset:29440
	v_add_f32_dpp v142, v142, v142 quad_perm:[2,3,0,1] row_mask:0xf bank_mask:0xf bound_ctrl:1
	v_add_f32_dpp v143, v143, v143 quad_perm:[2,3,0,1] row_mask:0xf bank_mask:0xf bound_ctrl:1
	ds_read_b128 v[182:185], v124 offset:29696
	v_add_f32_dpp v142, v142, v142 row_half_mirror row_mask:0xf bank_mask:0xf bound_ctrl:1
	v_add_f32_dpp v143, v143, v143 row_half_mirror row_mask:0xf bank_mask:0xf bound_ctrl:1
	ds_read_b128 v[186:189], v124 offset:29712
	ds_read_b128 v[190:193], v124 offset:29952
	ds_read_b128 v[194:197], v124 offset:29968
	ds_read_b128 v[144:147], v124 offset:29184
	ds_read_b128 v[148:151], v124 offset:29200
	v_pk_mul_f32 v[68:69], v[68:69], v[142:143] op_sel_hi:[1,0]
	v_pk_mul_f32 v[70:71], v[70:71], v[142:143] op_sel_hi:[1,0]
	s_lshl_b64 vcc, vcc, 1
	v_pk_mul_f32 v[56:57], v[56:57], v[142:143] op_sel_hi:[1,0]
	v_pk_mul_f32 v[58:59], v[58:59], v[142:143] op_sel_hi:[1,0]
	v_pk_fma_f32 v[64:65], v[64:65], v[126:127], v[68:69] op_sel_hi:[1,0,1] neg_lo:[0,0,1] neg_hi:[0,0,1]
	v_pk_fma_f32 v[66:67], v[66:67], v[126:127], v[70:71] op_sel_hi:[1,0,1] neg_lo:[0,0,1] neg_hi:[0,0,1]
	v_cndmask_b32_e32 v132, v132, v143, vcc
	v_pk_fma_f32 v[60:61], v[60:61], v[126:127], v[56:57] op_sel_hi:[1,0,1] neg_lo:[0,0,1] neg_hi:[0,0,1]
	v_pk_fma_f32 v[62:63], v[62:63], v[126:127], v[58:59] op_sel_hi:[1,0,1] neg_lo:[0,0,1] neg_hi:[0,0,1]
	ds_read_b128 v[202:205], v124 offset:30224
	ds_read_b128 v[198:201], v124 offset:30208
	v_pk_fma_f32 v[36:37], v[36:37], v[48:49], v[64:65]
	v_pk_fma_f32 v[38:39], v[38:39], v[50:51], v[66:67]
	v_pk_fma_f32 v[32:33], v[32:33], v[40:41], v[60:61]
	v_pk_fma_f32 v[34:35], v[34:35], v[42:43], v[62:63]
	s_waitcnt lgkmcnt(2)
	v_pk_mul_f32 v[156:157], v[32:33], v[156:157]
	v_pk_mul_f32 v[52:53], v[32:33], v[52:53]
	v_pk_mul_f32 v[158:159], v[34:35], v[158:159]
	v_pk_mul_f32 v[54:55], v[34:35], v[54:55]
	v_pk_fma_f32 v[152:153], v[36:37], v[152:153], v[156:157]
	v_pk_fma_f32 v[44:45], v[36:37], v[44:45], v[52:53]
	v_pk_fma_f32 v[154:155], v[38:39], v[154:155], v[158:159]
	v_pk_fma_f32 v[46:47], v[38:39], v[46:47], v[54:55]
	v_pk_add_f32 v[152:153], v[152:153], v[154:155]
	v_pk_add_f32 v[44:45], v[44:45], v[46:47]
	v_add_f32_e32 v142, v152, v153
	v_add_f32_e32 v143, v44, v45
	ds_read_b128 v[76:79], v124 offset:30992
	v_add_f32_dpp v142, v142, v142 quad_perm:[1,0,3,2] row_mask:0xf bank_mask:0xf bound_ctrl:1
	v_add_f32_dpp v143, v143, v143 quad_perm:[1,0,3,2] row_mask:0xf bank_mask:0xf bound_ctrl:1
	ds_read_b128 v[72:75], v124 offset:30976
	v_add_f32_dpp v142, v142, v142 quad_perm:[2,3,0,1] row_mask:0xf bank_mask:0xf bound_ctrl:1
	v_add_f32_dpp v143, v143, v143 quad_perm:[2,3,0,1] row_mask:0xf bank_mask:0xf bound_ctrl:1
	ds_read_b128 v[68:71], v124 offset:31232
	v_add_f32_dpp v142, v142, v142 row_half_mirror row_mask:0xf bank_mask:0xf bound_ctrl:1
	v_add_f32_dpp v143, v143, v143 row_half_mirror row_mask:0xf bank_mask:0xf bound_ctrl:1
	ds_read_b128 v[56:59], v124 offset:31248
	ds_read2st64_b32 v[160:161], v135 offset0:125 offset1:131
	ds_read_b128 v[64:67], v124 offset:31488
	ds_read_b128 v[60:63], v124 offset:31504
	ds_read_b128 v[48:51], v124 offset:30720
	ds_read_b128 v[40:43], v124 offset:30736
	v_pk_mul_f32 v[182:183], v[182:183], v[142:143] op_sel_hi:[1,0]
	v_pk_mul_f32 v[184:185], v[184:185], v[142:143] op_sel_hi:[1,0]
	s_lshl_b64 vcc, vcc, 1
	v_pk_mul_f32 v[186:187], v[186:187], v[142:143] op_sel_hi:[1,0]
	v_pk_mul_f32 v[188:189], v[188:189], v[142:143] op_sel_hi:[1,0]
	v_pk_fma_f32 v[190:191], v[190:191], v[126:127], v[182:183] op_sel:[0,1,0] op_sel_hi:[1,1,1] neg_lo:[0,0,1] neg_hi:[0,0,1]
	v_pk_fma_f32 v[192:193], v[192:193], v[126:127], v[184:185] op_sel:[0,1,0] op_sel_hi:[1,1,1] neg_lo:[0,0,1] neg_hi:[0,0,1]
	v_cndmask_b32_e32 v132, v132, v143, vcc
	v_pk_fma_f32 v[194:195], v[194:195], v[126:127], v[186:187] op_sel:[0,1,0] op_sel_hi:[1,1,1] neg_lo:[0,0,1] neg_hi:[0,0,1]
	v_pk_fma_f32 v[196:197], v[196:197], v[126:127], v[188:189] op_sel:[0,1,0] op_sel_hi:[1,1,1] neg_lo:[0,0,1] neg_hi:[0,0,1]
	ds_read_b128 v[52:55], v124 offset:31760
	ds_read_b128 v[44:47], v124 offset:31744
	v_pk_fma_f32 v[36:37], v[36:37], v[144:145], v[190:191]
	v_pk_fma_f32 v[38:39], v[38:39], v[146:147], v[192:193]
	v_pk_fma_f32 v[32:33], v[32:33], v[148:149], v[194:195]
	v_pk_fma_f32 v[34:35], v[34:35], v[150:151], v[196:197]
	s_waitcnt lgkmcnt(2)
	v_pk_mul_f32 v[76:77], v[32:33], v[76:77]
	v_pk_mul_f32 v[202:203], v[32:33], v[202:203]
	v_pk_mul_f32 v[78:79], v[34:35], v[78:79]
	v_pk_mul_f32 v[204:205], v[34:35], v[204:205]
	v_pk_fma_f32 v[72:73], v[36:37], v[72:73], v[76:77]
	v_pk_fma_f32 v[198:199], v[36:37], v[198:199], v[202:203]
	v_pk_fma_f32 v[74:75], v[38:39], v[74:75], v[78:79]
	v_pk_fma_f32 v[200:201], v[38:39], v[200:201], v[204:205]
	v_pk_add_f32 v[72:73], v[72:73], v[74:75]
	v_pk_add_f32 v[198:199], v[198:199], v[200:201]
	v_add_f32_e32 v142, v72, v73
	v_add_f32_e32 v143, v198, v199
	ds_read_b128 v[156:159], v124 offset:32528
	v_add_f32_dpp v142, v142, v142 quad_perm:[1,0,3,2] row_mask:0xf bank_mask:0xf bound_ctrl:1
	v_add_f32_dpp v143, v143, v143 quad_perm:[1,0,3,2] row_mask:0xf bank_mask:0xf bound_ctrl:1
	ds_read_b128 v[152:155], v124 offset:32512
	v_add_f32_dpp v142, v142, v142 quad_perm:[2,3,0,1] row_mask:0xf bank_mask:0xf bound_ctrl:1
	v_add_f32_dpp v143, v143, v143 quad_perm:[2,3,0,1] row_mask:0xf bank_mask:0xf bound_ctrl:1
	ds_read_b128 v[182:185], v124 offset:32768
	v_add_f32_dpp v142, v142, v142 row_half_mirror row_mask:0xf bank_mask:0xf bound_ctrl:1
	v_add_f32_dpp v143, v143, v143 row_half_mirror row_mask:0xf bank_mask:0xf bound_ctrl:1
	ds_read_b128 v[186:189], v124 offset:32784
	ds_read_b128 v[190:193], v124 offset:33024
	ds_read_b128 v[194:197], v124 offset:33040
	ds_read_b128 v[144:147], v124 offset:32256
	ds_read_b128 v[148:151], v124 offset:32272
	v_pk_mul_f32 v[68:69], v[68:69], v[142:143] op_sel_hi:[1,0]
	v_pk_mul_f32 v[70:71], v[70:71], v[142:143] op_sel_hi:[1,0]
	s_lshl_b64 vcc, vcc, 1
	v_pk_mul_f32 v[56:57], v[56:57], v[142:143] op_sel_hi:[1,0]
	v_pk_mul_f32 v[58:59], v[58:59], v[142:143] op_sel_hi:[1,0]
	v_pk_fma_f32 v[64:65], v[64:65], v[160:161], v[68:69] op_sel_hi:[1,0,1] neg_lo:[0,0,1] neg_hi:[0,0,1]
	v_pk_fma_f32 v[66:67], v[66:67], v[160:161], v[70:71] op_sel_hi:[1,0,1] neg_lo:[0,0,1] neg_hi:[0,0,1]
	v_cndmask_b32_e32 v132, v132, v143, vcc
	v_pk_fma_f32 v[60:61], v[60:61], v[160:161], v[56:57] op_sel_hi:[1,0,1] neg_lo:[0,0,1] neg_hi:[0,0,1]
	v_pk_fma_f32 v[62:63], v[62:63], v[160:161], v[58:59] op_sel_hi:[1,0,1] neg_lo:[0,0,1] neg_hi:[0,0,1]
	ds_read_b128 v[202:205], v124 offset:33296
	ds_read_b128 v[198:201], v124 offset:33280
	v_pk_fma_f32 v[36:37], v[36:37], v[48:49], v[64:65]
	v_pk_fma_f32 v[38:39], v[38:39], v[50:51], v[66:67]
	v_pk_fma_f32 v[32:33], v[32:33], v[40:41], v[60:61]
	v_pk_fma_f32 v[34:35], v[34:35], v[42:43], v[62:63]
	s_waitcnt lgkmcnt(2)
	v_pk_mul_f32 v[156:157], v[32:33], v[156:157]
	v_pk_mul_f32 v[52:53], v[32:33], v[52:53]
	v_pk_mul_f32 v[158:159], v[34:35], v[158:159]
	v_pk_mul_f32 v[54:55], v[34:35], v[54:55]
	v_pk_fma_f32 v[152:153], v[36:37], v[152:153], v[156:157]
	v_pk_fma_f32 v[44:45], v[36:37], v[44:45], v[52:53]
	v_pk_fma_f32 v[154:155], v[38:39], v[154:155], v[158:159]
	v_pk_fma_f32 v[46:47], v[38:39], v[46:47], v[54:55]
	v_pk_add_f32 v[152:153], v[152:153], v[154:155]
	v_pk_add_f32 v[44:45], v[44:45], v[46:47]
	v_add_f32_e32 v142, v152, v153
	v_add_f32_e32 v143, v44, v45
	ds_read_b128 v[76:79], v124 offset:34064
	v_add_f32_dpp v142, v142, v142 quad_perm:[1,0,3,2] row_mask:0xf bank_mask:0xf bound_ctrl:1
	v_add_f32_dpp v143, v143, v143 quad_perm:[1,0,3,2] row_mask:0xf bank_mask:0xf bound_ctrl:1
	ds_read_b128 v[72:75], v124 offset:34048
	v_add_f32_dpp v142, v142, v142 quad_perm:[2,3,0,1] row_mask:0xf bank_mask:0xf bound_ctrl:1
	v_add_f32_dpp v143, v143, v143 quad_perm:[2,3,0,1] row_mask:0xf bank_mask:0xf bound_ctrl:1
	ds_read_b128 v[68:71], v124 offset:34304
	v_add_f32_dpp v142, v142, v142 row_half_mirror row_mask:0xf bank_mask:0xf bound_ctrl:1
	v_add_f32_dpp v143, v143, v143 row_half_mirror row_mask:0xf bank_mask:0xf bound_ctrl:1
	ds_read_b128 v[56:59], v124 offset:34320
	ds_read2st64_b32 v[126:127], v135 offset0:137 offset1:143
	ds_read_b128 v[64:67], v124 offset:34560
	ds_read_b128 v[60:63], v124 offset:34576
	ds_read_b128 v[48:51], v124 offset:33792
	ds_read_b128 v[40:43], v124 offset:33808
	v_pk_mul_f32 v[182:183], v[182:183], v[142:143] op_sel_hi:[1,0]
	v_pk_mul_f32 v[184:185], v[184:185], v[142:143] op_sel_hi:[1,0]
	s_lshl_b64 vcc, vcc, 1
	v_pk_mul_f32 v[186:187], v[186:187], v[142:143] op_sel_hi:[1,0]
	v_pk_mul_f32 v[188:189], v[188:189], v[142:143] op_sel_hi:[1,0]
	v_pk_fma_f32 v[190:191], v[190:191], v[160:161], v[182:183] op_sel:[0,1,0] op_sel_hi:[1,1,1] neg_lo:[0,0,1] neg_hi:[0,0,1]
	v_pk_fma_f32 v[192:193], v[192:193], v[160:161], v[184:185] op_sel:[0,1,0] op_sel_hi:[1,1,1] neg_lo:[0,0,1] neg_hi:[0,0,1]
	v_cndmask_b32_e32 v132, v132, v143, vcc
	v_pk_fma_f32 v[194:195], v[194:195], v[160:161], v[186:187] op_sel:[0,1,0] op_sel_hi:[1,1,1] neg_lo:[0,0,1] neg_hi:[0,0,1]
	v_pk_fma_f32 v[196:197], v[196:197], v[160:161], v[188:189] op_sel:[0,1,0] op_sel_hi:[1,1,1] neg_lo:[0,0,1] neg_hi:[0,0,1]
	ds_read_b128 v[52:55], v124 offset:34832
	ds_read_b128 v[44:47], v124 offset:34816
	v_pk_fma_f32 v[36:37], v[36:37], v[144:145], v[190:191]
	v_pk_fma_f32 v[38:39], v[38:39], v[146:147], v[192:193]
	v_pk_fma_f32 v[32:33], v[32:33], v[148:149], v[194:195]
	v_pk_fma_f32 v[34:35], v[34:35], v[150:151], v[196:197]
	s_waitcnt lgkmcnt(2)
	v_pk_mul_f32 v[76:77], v[32:33], v[76:77]
	v_pk_mul_f32 v[202:203], v[32:33], v[202:203]
	v_pk_mul_f32 v[78:79], v[34:35], v[78:79]
	v_pk_mul_f32 v[204:205], v[34:35], v[204:205]
	v_pk_fma_f32 v[72:73], v[36:37], v[72:73], v[76:77]
	v_pk_fma_f32 v[198:199], v[36:37], v[198:199], v[202:203]
	v_pk_fma_f32 v[74:75], v[38:39], v[74:75], v[78:79]
	v_pk_fma_f32 v[200:201], v[38:39], v[200:201], v[204:205]
	v_pk_add_f32 v[72:73], v[72:73], v[74:75]
	v_pk_add_f32 v[198:199], v[198:199], v[200:201]
	v_add_f32_e32 v142, v72, v73
	v_add_f32_e32 v143, v198, v199
	ds_read_b128 v[156:159], v124 offset:35600
	v_add_f32_dpp v142, v142, v142 quad_perm:[1,0,3,2] row_mask:0xf bank_mask:0xf bound_ctrl:1
	v_add_f32_dpp v143, v143, v143 quad_perm:[1,0,3,2] row_mask:0xf bank_mask:0xf bound_ctrl:1
	ds_read_b128 v[152:155], v124 offset:35584
	v_add_f32_dpp v142, v142, v142 quad_perm:[2,3,0,1] row_mask:0xf bank_mask:0xf bound_ctrl:1
	v_add_f32_dpp v143, v143, v143 quad_perm:[2,3,0,1] row_mask:0xf bank_mask:0xf bound_ctrl:1
	ds_read_b128 v[182:185], v124 offset:35840
	v_add_f32_dpp v142, v142, v142 row_half_mirror row_mask:0xf bank_mask:0xf bound_ctrl:1
	v_add_f32_dpp v143, v143, v143 row_half_mirror row_mask:0xf bank_mask:0xf bound_ctrl:1
	ds_read_b128 v[186:189], v124 offset:35856
	ds_read_b128 v[190:193], v124 offset:36096
	ds_read_b128 v[194:197], v124 offset:36112
	ds_read_b128 v[144:147], v124 offset:35328
	ds_read_b128 v[148:151], v124 offset:35344
	v_pk_mul_f32 v[68:69], v[68:69], v[142:143] op_sel_hi:[1,0]
	v_pk_mul_f32 v[70:71], v[70:71], v[142:143] op_sel_hi:[1,0]
	s_lshl_b64 vcc, vcc, 1
	v_pk_mul_f32 v[56:57], v[56:57], v[142:143] op_sel_hi:[1,0]
	v_pk_mul_f32 v[58:59], v[58:59], v[142:143] op_sel_hi:[1,0]
	v_pk_fma_f32 v[64:65], v[64:65], v[126:127], v[68:69] op_sel_hi:[1,0,1] neg_lo:[0,0,1] neg_hi:[0,0,1]
	v_pk_fma_f32 v[66:67], v[66:67], v[126:127], v[70:71] op_sel_hi:[1,0,1] neg_lo:[0,0,1] neg_hi:[0,0,1]
	v_cndmask_b32_e32 v132, v132, v143, vcc
	v_pk_fma_f32 v[60:61], v[60:61], v[126:127], v[56:57] op_sel_hi:[1,0,1] neg_lo:[0,0,1] neg_hi:[0,0,1]
	v_pk_fma_f32 v[62:63], v[62:63], v[126:127], v[58:59] op_sel_hi:[1,0,1] neg_lo:[0,0,1] neg_hi:[0,0,1]
	ds_read_b128 v[202:205], v124 offset:36368
	ds_read_b128 v[198:201], v124 offset:36352
	v_pk_fma_f32 v[36:37], v[36:37], v[48:49], v[64:65]
	v_pk_fma_f32 v[38:39], v[38:39], v[50:51], v[66:67]
	v_pk_fma_f32 v[32:33], v[32:33], v[40:41], v[60:61]
	v_pk_fma_f32 v[34:35], v[34:35], v[42:43], v[62:63]
	s_waitcnt lgkmcnt(2)
	v_pk_mul_f32 v[156:157], v[32:33], v[156:157]
	v_pk_mul_f32 v[52:53], v[32:33], v[52:53]
	v_pk_mul_f32 v[158:159], v[34:35], v[158:159]
	v_pk_mul_f32 v[54:55], v[34:35], v[54:55]
	v_pk_fma_f32 v[152:153], v[36:37], v[152:153], v[156:157]
	v_pk_fma_f32 v[44:45], v[36:37], v[44:45], v[52:53]
	v_pk_fma_f32 v[154:155], v[38:39], v[154:155], v[158:159]
	v_pk_fma_f32 v[46:47], v[38:39], v[46:47], v[54:55]
	v_pk_add_f32 v[152:153], v[152:153], v[154:155]
	v_pk_add_f32 v[44:45], v[44:45], v[46:47]
	v_add_f32_e32 v142, v152, v153
	v_add_f32_e32 v143, v44, v45
	ds_read_b128 v[76:79], v124 offset:37136
	v_add_f32_dpp v142, v142, v142 quad_perm:[1,0,3,2] row_mask:0xf bank_mask:0xf bound_ctrl:1
	v_add_f32_dpp v143, v143, v143 quad_perm:[1,0,3,2] row_mask:0xf bank_mask:0xf bound_ctrl:1
	ds_read_b128 v[72:75], v124 offset:37120
	v_add_f32_dpp v142, v142, v142 quad_perm:[2,3,0,1] row_mask:0xf bank_mask:0xf bound_ctrl:1
	v_add_f32_dpp v143, v143, v143 quad_perm:[2,3,0,1] row_mask:0xf bank_mask:0xf bound_ctrl:1
	ds_read_b128 v[68:71], v124 offset:37376
	v_add_f32_dpp v142, v142, v142 row_half_mirror row_mask:0xf bank_mask:0xf bound_ctrl:1
	v_add_f32_dpp v143, v143, v143 row_half_mirror row_mask:0xf bank_mask:0xf bound_ctrl:1
	ds_read_b128 v[56:59], v124 offset:37392
	ds_read2st64_b32 v[160:161], v135 offset0:149 offset1:155
	ds_read_b128 v[64:67], v124 offset:37632
	ds_read_b128 v[60:63], v124 offset:37648
	ds_read_b128 v[48:51], v124 offset:36864
	ds_read_b128 v[40:43], v124 offset:36880
	v_pk_mul_f32 v[182:183], v[182:183], v[142:143] op_sel_hi:[1,0]
	v_pk_mul_f32 v[184:185], v[184:185], v[142:143] op_sel_hi:[1,0]
	s_lshl_b64 vcc, vcc, 1
	v_pk_mul_f32 v[186:187], v[186:187], v[142:143] op_sel_hi:[1,0]
	v_pk_mul_f32 v[188:189], v[188:189], v[142:143] op_sel_hi:[1,0]
	v_pk_fma_f32 v[190:191], v[190:191], v[126:127], v[182:183] op_sel:[0,1,0] op_sel_hi:[1,1,1] neg_lo:[0,0,1] neg_hi:[0,0,1]
	v_pk_fma_f32 v[192:193], v[192:193], v[126:127], v[184:185] op_sel:[0,1,0] op_sel_hi:[1,1,1] neg_lo:[0,0,1] neg_hi:[0,0,1]
	v_cndmask_b32_e32 v132, v132, v143, vcc
	v_pk_fma_f32 v[194:195], v[194:195], v[126:127], v[186:187] op_sel:[0,1,0] op_sel_hi:[1,1,1] neg_lo:[0,0,1] neg_hi:[0,0,1]
	v_pk_fma_f32 v[196:197], v[196:197], v[126:127], v[188:189] op_sel:[0,1,0] op_sel_hi:[1,1,1] neg_lo:[0,0,1] neg_hi:[0,0,1]
	ds_read_b128 v[52:55], v124 offset:37904
	ds_read_b128 v[44:47], v124 offset:37888
	v_pk_fma_f32 v[36:37], v[36:37], v[144:145], v[190:191]
	v_pk_fma_f32 v[38:39], v[38:39], v[146:147], v[192:193]
	v_pk_fma_f32 v[32:33], v[32:33], v[148:149], v[194:195]
	v_pk_fma_f32 v[34:35], v[34:35], v[150:151], v[196:197]
	s_waitcnt lgkmcnt(2)
	v_pk_mul_f32 v[76:77], v[32:33], v[76:77]
	v_pk_mul_f32 v[202:203], v[32:33], v[202:203]
	v_pk_mul_f32 v[78:79], v[34:35], v[78:79]
	v_pk_mul_f32 v[204:205], v[34:35], v[204:205]
	v_pk_fma_f32 v[72:73], v[36:37], v[72:73], v[76:77]
	v_pk_fma_f32 v[198:199], v[36:37], v[198:199], v[202:203]
	v_pk_fma_f32 v[74:75], v[38:39], v[74:75], v[78:79]
	v_pk_fma_f32 v[200:201], v[38:39], v[200:201], v[204:205]
	v_pk_add_f32 v[72:73], v[72:73], v[74:75]
	v_pk_add_f32 v[198:199], v[198:199], v[200:201]
	v_add_f32_e32 v142, v72, v73
	v_add_f32_e32 v143, v198, v199
	ds_read_b128 v[156:159], v124 offset:38672
	v_add_f32_dpp v142, v142, v142 quad_perm:[1,0,3,2] row_mask:0xf bank_mask:0xf bound_ctrl:1
	v_add_f32_dpp v143, v143, v143 quad_perm:[1,0,3,2] row_mask:0xf bank_mask:0xf bound_ctrl:1
	ds_read_b128 v[152:155], v124 offset:38656
	v_add_f32_dpp v142, v142, v142 quad_perm:[2,3,0,1] row_mask:0xf bank_mask:0xf bound_ctrl:1
	v_add_f32_dpp v143, v143, v143 quad_perm:[2,3,0,1] row_mask:0xf bank_mask:0xf bound_ctrl:1
	ds_read_b128 v[182:185], v124 offset:38912
	v_add_f32_dpp v142, v142, v142 row_half_mirror row_mask:0xf bank_mask:0xf bound_ctrl:1
	v_add_f32_dpp v143, v143, v143 row_half_mirror row_mask:0xf bank_mask:0xf bound_ctrl:1
	ds_read_b128 v[186:189], v124 offset:38928
	ds_read_b128 v[190:193], v124 offset:39168
	ds_read_b128 v[194:197], v124 offset:39184
	ds_read_b128 v[144:147], v124 offset:38400
	ds_read_b128 v[148:151], v124 offset:38416
	v_pk_mul_f32 v[68:69], v[68:69], v[142:143] op_sel_hi:[1,0]
	v_pk_mul_f32 v[70:71], v[70:71], v[142:143] op_sel_hi:[1,0]
	s_lshl_b64 vcc, vcc, 1
	v_pk_mul_f32 v[56:57], v[56:57], v[142:143] op_sel_hi:[1,0]
	v_pk_mul_f32 v[58:59], v[58:59], v[142:143] op_sel_hi:[1,0]
	v_pk_fma_f32 v[64:65], v[64:65], v[160:161], v[68:69] op_sel_hi:[1,0,1] neg_lo:[0,0,1] neg_hi:[0,0,1]
	v_pk_fma_f32 v[66:67], v[66:67], v[160:161], v[70:71] op_sel_hi:[1,0,1] neg_lo:[0,0,1] neg_hi:[0,0,1]
	v_cndmask_b32_e32 v132, v132, v143, vcc
	v_pk_fma_f32 v[60:61], v[60:61], v[160:161], v[56:57] op_sel_hi:[1,0,1] neg_lo:[0,0,1] neg_hi:[0,0,1]
	v_pk_fma_f32 v[62:63], v[62:63], v[160:161], v[58:59] op_sel_hi:[1,0,1] neg_lo:[0,0,1] neg_hi:[0,0,1]
	ds_read_b128 v[202:205], v124 offset:39440
	ds_read_b128 v[198:201], v124 offset:39424
	v_pk_fma_f32 v[36:37], v[36:37], v[48:49], v[64:65]
	v_pk_fma_f32 v[38:39], v[38:39], v[50:51], v[66:67]
	v_pk_fma_f32 v[32:33], v[32:33], v[40:41], v[60:61]
	v_pk_fma_f32 v[34:35], v[34:35], v[42:43], v[62:63]
	s_waitcnt lgkmcnt(2)
	v_pk_mul_f32 v[156:157], v[32:33], v[156:157]
	v_pk_mul_f32 v[52:53], v[32:33], v[52:53]
	v_pk_mul_f32 v[158:159], v[34:35], v[158:159]
	v_pk_mul_f32 v[54:55], v[34:35], v[54:55]
	v_pk_fma_f32 v[152:153], v[36:37], v[152:153], v[156:157]
	v_pk_fma_f32 v[44:45], v[36:37], v[44:45], v[52:53]
	v_pk_fma_f32 v[154:155], v[38:39], v[154:155], v[158:159]
	v_pk_fma_f32 v[46:47], v[38:39], v[46:47], v[54:55]
	v_pk_add_f32 v[152:153], v[152:153], v[154:155]
	v_pk_add_f32 v[44:45], v[44:45], v[46:47]
	v_add_f32_e32 v142, v152, v153
	v_add_f32_e32 v143, v44, v45
	ds_read_b128 v[76:79], v124 offset:40208
	v_add_f32_dpp v142, v142, v142 quad_perm:[1,0,3,2] row_mask:0xf bank_mask:0xf bound_ctrl:1
	v_add_f32_dpp v143, v143, v143 quad_perm:[1,0,3,2] row_mask:0xf bank_mask:0xf bound_ctrl:1
	ds_read_b128 v[72:75], v124 offset:40192
	v_add_f32_dpp v142, v142, v142 quad_perm:[2,3,0,1] row_mask:0xf bank_mask:0xf bound_ctrl:1
	v_add_f32_dpp v143, v143, v143 quad_perm:[2,3,0,1] row_mask:0xf bank_mask:0xf bound_ctrl:1
	ds_read_b128 v[68:71], v124 offset:40448
	v_add_f32_dpp v142, v142, v142 row_half_mirror row_mask:0xf bank_mask:0xf bound_ctrl:1
	v_add_f32_dpp v143, v143, v143 row_half_mirror row_mask:0xf bank_mask:0xf bound_ctrl:1
	ds_read_b128 v[56:59], v124 offset:40464
	ds_read2st64_b32 v[126:127], v135 offset0:161 offset1:167
	ds_read_b128 v[64:67], v124 offset:40704
	ds_read_b128 v[60:63], v124 offset:40720
	ds_read_b128 v[48:51], v124 offset:39936
	ds_read_b128 v[40:43], v124 offset:39952
	v_pk_mul_f32 v[182:183], v[182:183], v[142:143] op_sel_hi:[1,0]
	v_pk_mul_f32 v[184:185], v[184:185], v[142:143] op_sel_hi:[1,0]
	s_mov_b32 vcc_lo, 0x1010101
	v_pk_mul_f32 v[186:187], v[186:187], v[142:143] op_sel_hi:[1,0]
	v_pk_mul_f32 v[188:189], v[188:189], v[142:143] op_sel_hi:[1,0]
	s_mov_b32 vcc_hi, 0x1010101
	v_pk_fma_f32 v[190:191], v[190:191], v[160:161], v[182:183] op_sel:[0,1,0] op_sel_hi:[1,1,1] neg_lo:[0,0,1] neg_hi:[0,0,1]
	v_pk_fma_f32 v[192:193], v[192:193], v[160:161], v[184:185] op_sel:[0,1,0] op_sel_hi:[1,1,1] neg_lo:[0,0,1] neg_hi:[0,0,1]
	v_cndmask_b32_e32 v131, v131, v143, vcc
	v_pk_fma_f32 v[194:195], v[194:195], v[160:161], v[186:187] op_sel:[0,1,0] op_sel_hi:[1,1,1] neg_lo:[0,0,1] neg_hi:[0,0,1]
	v_pk_fma_f32 v[196:197], v[196:197], v[160:161], v[188:189] op_sel:[0,1,0] op_sel_hi:[1,1,1] neg_lo:[0,0,1] neg_hi:[0,0,1]
	ds_read_b128 v[52:55], v124 offset:40976
	ds_read_b128 v[44:47], v124 offset:40960
	v_pk_fma_f32 v[36:37], v[36:37], v[144:145], v[190:191]
	v_pk_fma_f32 v[38:39], v[38:39], v[146:147], v[192:193]
	v_pk_fma_f32 v[32:33], v[32:33], v[148:149], v[194:195]
	v_pk_fma_f32 v[34:35], v[34:35], v[150:151], v[196:197]
	s_waitcnt lgkmcnt(2)
	v_pk_mul_f32 v[76:77], v[32:33], v[76:77]
	v_pk_mul_f32 v[202:203], v[32:33], v[202:203]
	v_pk_mul_f32 v[78:79], v[34:35], v[78:79]
	v_pk_mul_f32 v[204:205], v[34:35], v[204:205]
	v_pk_fma_f32 v[72:73], v[36:37], v[72:73], v[76:77]
	v_pk_fma_f32 v[198:199], v[36:37], v[198:199], v[202:203]
	v_pk_fma_f32 v[74:75], v[38:39], v[74:75], v[78:79]
	v_pk_fma_f32 v[200:201], v[38:39], v[200:201], v[204:205]
	v_pk_add_f32 v[72:73], v[72:73], v[74:75]
	v_pk_add_f32 v[198:199], v[198:199], v[200:201]
	v_add_f32_e32 v142, v72, v73
	v_add_f32_e32 v143, v198, v199
	ds_read_b128 v[156:159], v124 offset:41744
	v_add_f32_dpp v142, v142, v142 quad_perm:[1,0,3,2] row_mask:0xf bank_mask:0xf bound_ctrl:1
	v_add_f32_dpp v143, v143, v143 quad_perm:[1,0,3,2] row_mask:0xf bank_mask:0xf bound_ctrl:1
	ds_read_b128 v[152:155], v124 offset:41728
	v_add_f32_dpp v142, v142, v142 quad_perm:[2,3,0,1] row_mask:0xf bank_mask:0xf bound_ctrl:1
	v_add_f32_dpp v143, v143, v143 quad_perm:[2,3,0,1] row_mask:0xf bank_mask:0xf bound_ctrl:1
	ds_read_b128 v[182:185], v124 offset:41984
	v_add_f32_dpp v142, v142, v142 row_half_mirror row_mask:0xf bank_mask:0xf bound_ctrl:1
	v_add_f32_dpp v143, v143, v143 row_half_mirror row_mask:0xf bank_mask:0xf bound_ctrl:1
	ds_read_b128 v[186:189], v124 offset:42000
	ds_read_b128 v[190:193], v124 offset:42240
	ds_read_b128 v[194:197], v124 offset:42256
	ds_read_b128 v[144:147], v124 offset:41472
	ds_read_b128 v[148:151], v124 offset:41488
	v_pk_mul_f32 v[68:69], v[68:69], v[142:143] op_sel_hi:[1,0]
	v_pk_mul_f32 v[70:71], v[70:71], v[142:143] op_sel_hi:[1,0]
	s_lshl_b64 vcc, vcc, 1
	v_pk_mul_f32 v[56:57], v[56:57], v[142:143] op_sel_hi:[1,0]
	v_pk_mul_f32 v[58:59], v[58:59], v[142:143] op_sel_hi:[1,0]
	v_pk_fma_f32 v[64:65], v[64:65], v[126:127], v[68:69] op_sel_hi:[1,0,1] neg_lo:[0,0,1] neg_hi:[0,0,1]
	v_pk_fma_f32 v[66:67], v[66:67], v[126:127], v[70:71] op_sel_hi:[1,0,1] neg_lo:[0,0,1] neg_hi:[0,0,1]
	v_cndmask_b32_e32 v131, v131, v143, vcc
	v_pk_fma_f32 v[60:61], v[60:61], v[126:127], v[56:57] op_sel_hi:[1,0,1] neg_lo:[0,0,1] neg_hi:[0,0,1]
	v_pk_fma_f32 v[62:63], v[62:63], v[126:127], v[58:59] op_sel_hi:[1,0,1] neg_lo:[0,0,1] neg_hi:[0,0,1]
	ds_read_b128 v[202:205], v124 offset:42512
	ds_read_b128 v[198:201], v124 offset:42496
	v_pk_fma_f32 v[36:37], v[36:37], v[48:49], v[64:65]
	v_pk_fma_f32 v[38:39], v[38:39], v[50:51], v[66:67]
	v_pk_fma_f32 v[32:33], v[32:33], v[40:41], v[60:61]
	v_pk_fma_f32 v[34:35], v[34:35], v[42:43], v[62:63]
	s_waitcnt lgkmcnt(2)
	v_pk_mul_f32 v[156:157], v[32:33], v[156:157]
	v_pk_mul_f32 v[52:53], v[32:33], v[52:53]
	v_pk_mul_f32 v[158:159], v[34:35], v[158:159]
	v_pk_mul_f32 v[54:55], v[34:35], v[54:55]
	v_pk_fma_f32 v[152:153], v[36:37], v[152:153], v[156:157]
	v_pk_fma_f32 v[44:45], v[36:37], v[44:45], v[52:53]
	v_pk_fma_f32 v[154:155], v[38:39], v[154:155], v[158:159]
	v_pk_fma_f32 v[46:47], v[38:39], v[46:47], v[54:55]
	v_pk_add_f32 v[152:153], v[152:153], v[154:155]
	v_pk_add_f32 v[44:45], v[44:45], v[46:47]
	v_add_f32_e32 v142, v152, v153
	v_add_f32_e32 v143, v44, v45
	ds_read_b128 v[76:79], v124 offset:43280
	v_add_f32_dpp v142, v142, v142 quad_perm:[1,0,3,2] row_mask:0xf bank_mask:0xf bound_ctrl:1
	v_add_f32_dpp v143, v143, v143 quad_perm:[1,0,3,2] row_mask:0xf bank_mask:0xf bound_ctrl:1
	ds_read_b128 v[72:75], v124 offset:43264
	v_add_f32_dpp v142, v142, v142 quad_perm:[2,3,0,1] row_mask:0xf bank_mask:0xf bound_ctrl:1
	v_add_f32_dpp v143, v143, v143 quad_perm:[2,3,0,1] row_mask:0xf bank_mask:0xf bound_ctrl:1
	ds_read_b128 v[68:71], v124 offset:43520
	v_add_f32_dpp v142, v142, v142 row_half_mirror row_mask:0xf bank_mask:0xf bound_ctrl:1
	v_add_f32_dpp v143, v143, v143 row_half_mirror row_mask:0xf bank_mask:0xf bound_ctrl:1
	ds_read_b128 v[56:59], v124 offset:43536
	ds_read2st64_b32 v[160:161], v135 offset0:173 offset1:179
	ds_read_b128 v[64:67], v124 offset:43776
	ds_read_b128 v[60:63], v124 offset:43792
	ds_read_b128 v[48:51], v124 offset:43008
	ds_read_b128 v[40:43], v124 offset:43024
	v_pk_mul_f32 v[182:183], v[182:183], v[142:143] op_sel_hi:[1,0]
	v_pk_mul_f32 v[184:185], v[184:185], v[142:143] op_sel_hi:[1,0]
	s_lshl_b64 vcc, vcc, 1
	v_pk_mul_f32 v[186:187], v[186:187], v[142:143] op_sel_hi:[1,0]
	v_pk_mul_f32 v[188:189], v[188:189], v[142:143] op_sel_hi:[1,0]
	v_pk_fma_f32 v[190:191], v[190:191], v[126:127], v[182:183] op_sel:[0,1,0] op_sel_hi:[1,1,1] neg_lo:[0,0,1] neg_hi:[0,0,1]
	v_pk_fma_f32 v[192:193], v[192:193], v[126:127], v[184:185] op_sel:[0,1,0] op_sel_hi:[1,1,1] neg_lo:[0,0,1] neg_hi:[0,0,1]
	v_cndmask_b32_e32 v131, v131, v143, vcc
	v_pk_fma_f32 v[194:195], v[194:195], v[126:127], v[186:187] op_sel:[0,1,0] op_sel_hi:[1,1,1] neg_lo:[0,0,1] neg_hi:[0,0,1]
	v_pk_fma_f32 v[196:197], v[196:197], v[126:127], v[188:189] op_sel:[0,1,0] op_sel_hi:[1,1,1] neg_lo:[0,0,1] neg_hi:[0,0,1]
	ds_read_b128 v[52:55], v124 offset:44048
	ds_read_b128 v[44:47], v124 offset:44032
	v_pk_fma_f32 v[36:37], v[36:37], v[144:145], v[190:191]
	v_pk_fma_f32 v[38:39], v[38:39], v[146:147], v[192:193]
	v_pk_fma_f32 v[32:33], v[32:33], v[148:149], v[194:195]
	v_pk_fma_f32 v[34:35], v[34:35], v[150:151], v[196:197]
	s_waitcnt lgkmcnt(2)
	v_pk_mul_f32 v[76:77], v[32:33], v[76:77]
	v_pk_mul_f32 v[202:203], v[32:33], v[202:203]
	v_pk_mul_f32 v[78:79], v[34:35], v[78:79]
	v_pk_mul_f32 v[204:205], v[34:35], v[204:205]
	v_pk_fma_f32 v[72:73], v[36:37], v[72:73], v[76:77]
	v_pk_fma_f32 v[198:199], v[36:37], v[198:199], v[202:203]
	v_pk_fma_f32 v[74:75], v[38:39], v[74:75], v[78:79]
	v_pk_fma_f32 v[200:201], v[38:39], v[200:201], v[204:205]
	v_pk_add_f32 v[72:73], v[72:73], v[74:75]
	v_pk_add_f32 v[198:199], v[198:199], v[200:201]
	v_add_f32_e32 v142, v72, v73
	v_add_f32_e32 v143, v198, v199
	ds_read_b128 v[156:159], v124 offset:44816
	v_add_f32_dpp v142, v142, v142 quad_perm:[1,0,3,2] row_mask:0xf bank_mask:0xf bound_ctrl:1
	v_add_f32_dpp v143, v143, v143 quad_perm:[1,0,3,2] row_mask:0xf bank_mask:0xf bound_ctrl:1
	ds_read_b128 v[152:155], v124 offset:44800
	v_add_f32_dpp v142, v142, v142 quad_perm:[2,3,0,1] row_mask:0xf bank_mask:0xf bound_ctrl:1
	v_add_f32_dpp v143, v143, v143 quad_perm:[2,3,0,1] row_mask:0xf bank_mask:0xf bound_ctrl:1
	ds_read_b128 v[182:185], v124 offset:45056
	v_add_f32_dpp v142, v142, v142 row_half_mirror row_mask:0xf bank_mask:0xf bound_ctrl:1
	v_add_f32_dpp v143, v143, v143 row_half_mirror row_mask:0xf bank_mask:0xf bound_ctrl:1
	ds_read_b128 v[186:189], v124 offset:45072
	ds_read_b128 v[190:193], v124 offset:45312
	ds_read_b128 v[194:197], v124 offset:45328
	ds_read_b128 v[144:147], v124 offset:44544
	ds_read_b128 v[148:151], v124 offset:44560
	v_pk_mul_f32 v[68:69], v[68:69], v[142:143] op_sel_hi:[1,0]
	v_pk_mul_f32 v[70:71], v[70:71], v[142:143] op_sel_hi:[1,0]
	s_lshl_b64 vcc, vcc, 1
	v_pk_mul_f32 v[56:57], v[56:57], v[142:143] op_sel_hi:[1,0]
	v_pk_mul_f32 v[58:59], v[58:59], v[142:143] op_sel_hi:[1,0]
	v_pk_fma_f32 v[64:65], v[64:65], v[160:161], v[68:69] op_sel_hi:[1,0,1] neg_lo:[0,0,1] neg_hi:[0,0,1]
	v_pk_fma_f32 v[66:67], v[66:67], v[160:161], v[70:71] op_sel_hi:[1,0,1] neg_lo:[0,0,1] neg_hi:[0,0,1]
	v_cndmask_b32_e32 v131, v131, v143, vcc
	v_pk_fma_f32 v[60:61], v[60:61], v[160:161], v[56:57] op_sel_hi:[1,0,1] neg_lo:[0,0,1] neg_hi:[0,0,1]
	v_pk_fma_f32 v[62:63], v[62:63], v[160:161], v[58:59] op_sel_hi:[1,0,1] neg_lo:[0,0,1] neg_hi:[0,0,1]
	ds_read_b128 v[202:205], v124 offset:45584
	ds_read_b128 v[198:201], v124 offset:45568
	v_pk_fma_f32 v[36:37], v[36:37], v[48:49], v[64:65]
	v_pk_fma_f32 v[38:39], v[38:39], v[50:51], v[66:67]
	v_pk_fma_f32 v[32:33], v[32:33], v[40:41], v[60:61]
	v_pk_fma_f32 v[34:35], v[34:35], v[42:43], v[62:63]
	s_waitcnt lgkmcnt(2)
	v_pk_mul_f32 v[156:157], v[32:33], v[156:157]
	v_pk_mul_f32 v[52:53], v[32:33], v[52:53]
	v_pk_mul_f32 v[158:159], v[34:35], v[158:159]
	v_pk_mul_f32 v[54:55], v[34:35], v[54:55]
	v_pk_fma_f32 v[152:153], v[36:37], v[152:153], v[156:157]
	v_pk_fma_f32 v[44:45], v[36:37], v[44:45], v[52:53]
	v_pk_fma_f32 v[154:155], v[38:39], v[154:155], v[158:159]
	v_pk_fma_f32 v[46:47], v[38:39], v[46:47], v[54:55]
	v_pk_add_f32 v[152:153], v[152:153], v[154:155]
	v_pk_add_f32 v[44:45], v[44:45], v[46:47]
	v_add_f32_e32 v142, v152, v153
	v_add_f32_e32 v143, v44, v45
	ds_read_b128 v[76:79], v124 offset:46352
	v_add_f32_dpp v142, v142, v142 quad_perm:[1,0,3,2] row_mask:0xf bank_mask:0xf bound_ctrl:1
	v_add_f32_dpp v143, v143, v143 quad_perm:[1,0,3,2] row_mask:0xf bank_mask:0xf bound_ctrl:1
	ds_read_b128 v[72:75], v124 offset:46336
	v_add_f32_dpp v142, v142, v142 quad_perm:[2,3,0,1] row_mask:0xf bank_mask:0xf bound_ctrl:1
	v_add_f32_dpp v143, v143, v143 quad_perm:[2,3,0,1] row_mask:0xf bank_mask:0xf bound_ctrl:1
	ds_read_b128 v[68:71], v124 offset:46592
	v_add_f32_dpp v142, v142, v142 row_half_mirror row_mask:0xf bank_mask:0xf bound_ctrl:1
	v_add_f32_dpp v143, v143, v143 row_half_mirror row_mask:0xf bank_mask:0xf bound_ctrl:1
	ds_read_b128 v[56:59], v124 offset:46608
	ds_read2st64_b32 v[126:127], v135 offset0:185 offset1:191
	ds_read_b128 v[64:67], v124 offset:46848
	ds_read_b128 v[60:63], v124 offset:46864
	ds_read_b128 v[48:51], v124 offset:46080
	ds_read_b128 v[40:43], v124 offset:46096
	v_pk_mul_f32 v[182:183], v[182:183], v[142:143] op_sel_hi:[1,0]
	v_pk_mul_f32 v[184:185], v[184:185], v[142:143] op_sel_hi:[1,0]
	s_lshl_b64 vcc, vcc, 1
	v_pk_mul_f32 v[186:187], v[186:187], v[142:143] op_sel_hi:[1,0]
	v_pk_mul_f32 v[188:189], v[188:189], v[142:143] op_sel_hi:[1,0]
	v_pk_fma_f32 v[190:191], v[190:191], v[160:161], v[182:183] op_sel:[0,1,0] op_sel_hi:[1,1,1] neg_lo:[0,0,1] neg_hi:[0,0,1]
	v_pk_fma_f32 v[192:193], v[192:193], v[160:161], v[184:185] op_sel:[0,1,0] op_sel_hi:[1,1,1] neg_lo:[0,0,1] neg_hi:[0,0,1]
	v_cndmask_b32_e32 v131, v131, v143, vcc
	v_pk_fma_f32 v[194:195], v[194:195], v[160:161], v[186:187] op_sel:[0,1,0] op_sel_hi:[1,1,1] neg_lo:[0,0,1] neg_hi:[0,0,1]
	v_pk_fma_f32 v[196:197], v[196:197], v[160:161], v[188:189] op_sel:[0,1,0] op_sel_hi:[1,1,1] neg_lo:[0,0,1] neg_hi:[0,0,1]
	ds_read_b128 v[52:55], v124 offset:47120
	ds_read_b128 v[44:47], v124 offset:47104
	v_pk_fma_f32 v[36:37], v[36:37], v[144:145], v[190:191]
	v_pk_fma_f32 v[38:39], v[38:39], v[146:147], v[192:193]
	v_pk_fma_f32 v[32:33], v[32:33], v[148:149], v[194:195]
	v_pk_fma_f32 v[34:35], v[34:35], v[150:151], v[196:197]
	s_waitcnt lgkmcnt(2)
	v_pk_mul_f32 v[76:77], v[32:33], v[76:77]
	v_pk_mul_f32 v[202:203], v[32:33], v[202:203]
	v_pk_mul_f32 v[78:79], v[34:35], v[78:79]
	v_pk_mul_f32 v[204:205], v[34:35], v[204:205]
	v_pk_fma_f32 v[72:73], v[36:37], v[72:73], v[76:77]
	v_pk_fma_f32 v[198:199], v[36:37], v[198:199], v[202:203]
	v_pk_fma_f32 v[74:75], v[38:39], v[74:75], v[78:79]
	v_pk_fma_f32 v[200:201], v[38:39], v[200:201], v[204:205]
	v_pk_add_f32 v[72:73], v[72:73], v[74:75]
	v_pk_add_f32 v[198:199], v[198:199], v[200:201]
	v_add_f32_e32 v142, v72, v73
	v_add_f32_e32 v143, v198, v199
	ds_read_b128 v[156:159], v124 offset:47888
	v_add_f32_dpp v142, v142, v142 quad_perm:[1,0,3,2] row_mask:0xf bank_mask:0xf bound_ctrl:1
	v_add_f32_dpp v143, v143, v143 quad_perm:[1,0,3,2] row_mask:0xf bank_mask:0xf bound_ctrl:1
	ds_read_b128 v[152:155], v124 offset:47872
	v_add_f32_dpp v142, v142, v142 quad_perm:[2,3,0,1] row_mask:0xf bank_mask:0xf bound_ctrl:1
	v_add_f32_dpp v143, v143, v143 quad_perm:[2,3,0,1] row_mask:0xf bank_mask:0xf bound_ctrl:1
	ds_read_b128 v[182:185], v124 offset:48128
	v_add_f32_dpp v142, v142, v142 row_half_mirror row_mask:0xf bank_mask:0xf bound_ctrl:1
	v_add_f32_dpp v143, v143, v143 row_half_mirror row_mask:0xf bank_mask:0xf bound_ctrl:1
	ds_read_b128 v[186:189], v124 offset:48144
	ds_read_b128 v[190:193], v124 offset:48384
	ds_read_b128 v[194:197], v124 offset:48400
	ds_read_b128 v[144:147], v124 offset:47616
	ds_read_b128 v[148:151], v124 offset:47632
	v_pk_mul_f32 v[68:69], v[68:69], v[142:143] op_sel_hi:[1,0]
	v_pk_mul_f32 v[70:71], v[70:71], v[142:143] op_sel_hi:[1,0]
	s_lshl_b64 vcc, vcc, 1
	v_pk_mul_f32 v[56:57], v[56:57], v[142:143] op_sel_hi:[1,0]
	v_pk_mul_f32 v[58:59], v[58:59], v[142:143] op_sel_hi:[1,0]
	v_pk_fma_f32 v[64:65], v[64:65], v[126:127], v[68:69] op_sel_hi:[1,0,1] neg_lo:[0,0,1] neg_hi:[0,0,1]
	v_pk_fma_f32 v[66:67], v[66:67], v[126:127], v[70:71] op_sel_hi:[1,0,1] neg_lo:[0,0,1] neg_hi:[0,0,1]
	v_cndmask_b32_e32 v131, v131, v143, vcc
	v_pk_fma_f32 v[60:61], v[60:61], v[126:127], v[56:57] op_sel_hi:[1,0,1] neg_lo:[0,0,1] neg_hi:[0,0,1]
	v_pk_fma_f32 v[62:63], v[62:63], v[126:127], v[58:59] op_sel_hi:[1,0,1] neg_lo:[0,0,1] neg_hi:[0,0,1]
	ds_read_b128 v[202:205], v124 offset:48656
	ds_read_b128 v[198:201], v124 offset:48640
	v_pk_fma_f32 v[36:37], v[36:37], v[48:49], v[64:65]
	v_pk_fma_f32 v[38:39], v[38:39], v[50:51], v[66:67]
	v_pk_fma_f32 v[32:33], v[32:33], v[40:41], v[60:61]
	v_pk_fma_f32 v[34:35], v[34:35], v[42:43], v[62:63]
	s_waitcnt lgkmcnt(2)
	v_pk_mul_f32 v[156:157], v[32:33], v[156:157]
	v_pk_mul_f32 v[52:53], v[32:33], v[52:53]
	v_pk_mul_f32 v[158:159], v[34:35], v[158:159]
	v_pk_mul_f32 v[54:55], v[34:35], v[54:55]
	v_pk_fma_f32 v[152:153], v[36:37], v[152:153], v[156:157]
	v_pk_fma_f32 v[44:45], v[36:37], v[44:45], v[52:53]
	v_pk_fma_f32 v[154:155], v[38:39], v[154:155], v[158:159]
	v_pk_fma_f32 v[46:47], v[38:39], v[46:47], v[54:55]
	v_pk_add_f32 v[152:153], v[152:153], v[154:155]
	v_pk_add_f32 v[44:45], v[44:45], v[46:47]
	v_add_f32_e32 v142, v152, v153
	v_add_f32_e32 v143, v44, v45
	s_nop 0
	v_add_f32_dpp v142, v142, v142 quad_perm:[1,0,3,2] row_mask:0xf bank_mask:0xf bound_ctrl:1
	v_add_f32_dpp v143, v143, v143 quad_perm:[1,0,3,2] row_mask:0xf bank_mask:0xf bound_ctrl:1
	s_nop 0
	v_add_f32_dpp v142, v142, v142 quad_perm:[2,3,0,1] row_mask:0xf bank_mask:0xf bound_ctrl:1
	v_add_f32_dpp v143, v143, v143 quad_perm:[2,3,0,1] row_mask:0xf bank_mask:0xf bound_ctrl:1
	s_nop 0
	v_add_f32_dpp v142, v142, v142 row_half_mirror row_mask:0xf bank_mask:0xf bound_ctrl:1
	v_add_f32_dpp v143, v143, v143 row_half_mirror row_mask:0xf bank_mask:0xf bound_ctrl:1
	v_pk_mul_f32 v[182:183], v[182:183], v[142:143] op_sel_hi:[1,0]
	v_pk_mul_f32 v[184:185], v[184:185], v[142:143] op_sel_hi:[1,0]
	s_lshl_b64 vcc, vcc, 1
	v_pk_mul_f32 v[186:187], v[186:187], v[142:143] op_sel_hi:[1,0]
	v_pk_mul_f32 v[188:189], v[188:189], v[142:143] op_sel_hi:[1,0]
	v_pk_fma_f32 v[190:191], v[190:191], v[126:127], v[182:183] op_sel:[0,1,0] op_sel_hi:[1,1,1] neg_lo:[0,0,1] neg_hi:[0,0,1]
	v_pk_fma_f32 v[192:193], v[192:193], v[126:127], v[184:185] op_sel:[0,1,0] op_sel_hi:[1,1,1] neg_lo:[0,0,1] neg_hi:[0,0,1]
	v_cndmask_b32_e32 v131, v131, v143, vcc
	v_pk_fma_f32 v[194:195], v[194:195], v[126:127], v[186:187] op_sel:[0,1,0] op_sel_hi:[1,1,1] neg_lo:[0,0,1] neg_hi:[0,0,1]
	v_pk_fma_f32 v[196:197], v[196:197], v[126:127], v[188:189] op_sel:[0,1,0] op_sel_hi:[1,1,1] neg_lo:[0,0,1] neg_hi:[0,0,1]
	v_pk_fma_f32 v[36:37], v[36:37], v[144:145], v[190:191]
	v_pk_fma_f32 v[38:39], v[38:39], v[146:147], v[192:193]
	v_pk_fma_f32 v[32:33], v[32:33], v[148:149], v[194:195]
	v_pk_fma_f32 v[34:35], v[34:35], v[150:151], v[196:197]
	s_waitcnt lgkmcnt(0)
	v_pk_mul_f32 v[202:203], v[32:33], v[202:203]
	v_pk_mul_f32 v[204:205], v[34:35], v[204:205]
	v_pk_fma_f32 v[198:199], v[36:37], v[198:199], v[202:203]
	v_pk_fma_f32 v[200:201], v[38:39], v[200:201], v[204:205]
	v_pk_add_f32 v[198:199], v[198:199], v[200:201]
	v_add_f32_e32 v143, v198, v199
	s_nop 1
	v_add_f32_dpp v143, v143, v143 quad_perm:[1,0,3,2] row_mask:0xf bank_mask:0xf bound_ctrl:1
	s_nop 1
	v_add_f32_dpp v143, v143, v143 quad_perm:[2,3,0,1] row_mask:0xf bank_mask:0xf bound_ctrl:1
	s_nop 1
	v_add_f32_dpp v143, v143, v143 row_half_mirror row_mask:0xf bank_mask:0xf bound_ctrl:1
	s_lshl_b64 vcc, vcc, 1
	v_cndmask_b32_e32 v131, v131, v143, vcc
	s_setprio 0
	s_add_i32 s70, s64, 1
	s_cmp_eq_u32 s70, s84
	s_cbranch_scc1 .Lrw_epi_last
	s_and_b32 s70, s64, 1
	s_mul_i32 s70, s70, 0x1200
	s_add_u32 s70, s70, 0x19000
	v_mad_u32_u24 v40, v86, 36, v81
	v_lshl_add_u32 v40, v40, 2, s70
	ds_write_b32 v40, v134
	ds_write_b32 v40, v133 offset:1152
	ds_write_b32 v40, v132 offset:2304
	ds_write_b32 v40, v131 offset:3456
	s_mov_b64 s[20:21], 0
	s_branch .LBB0_654
